# prep_tile item body rewritten by hand: batched loads, per-channel f32 parameter/mu loads issued by 4 lanes and row-broadcast with DPP (cuts L1 traffic); plus earlier norm/epilogue/mod_job edits
# speedup vs baseline: 1.0150x; 1.0129x over previous
_Z14fwd_megakernel6Params:
	v_mov_b32_e32 v1, 0
	v_writelane_b32 v233, s0, 62
	v_writelane_b32 v233, s1, 63
	global_load_dword v2, v1, s[0:1] offset:246
	s_load_dwordx4 s[24:27], s[0:1], 0xe0
	s_load_dword s28, s[0:1], 0xf0
	s_load_dwordx8 s[4:11], s[0:1], 0xc0
	s_add_u32 s94, s0, 0xe8
	v_and_b32_e32 v178, 0x3ff, v0
	s_addc_u32 s95, s1, 0
	v_cmp_eq_u32_e64 s[92:93], 0, v178
	s_waitcnt lgkmcnt(0)
	v_writelane_b32 v237, s4, 0
	s_waitcnt vmcnt(0)
	v_readfirstlane_b32 s29, v2
	v_writelane_b32 v237, s5, 1
	v_writelane_b32 v237, s6, 2
	v_writelane_b32 v237, s7, 3
	v_writelane_b32 v237, s8, 4
	v_writelane_b32 v237, s9, 5
	v_writelane_b32 v237, s10, 6
	v_writelane_b32 v237, s11, 7
	s_and_saveexec_b64 s[4:5], s[92:93]
	s_cbranch_execz .LBB0_2
	v_mov_b32_e32 v2, 0x10000
	ds_write_b32 v2, v1
	v_mov_b32_e32 v2, 0x10004
	ds_write_b32 v2, v1

.LBB0_332:
.Lprep2_entry:
	s_lshr_b32 s34, s13, 2
	v_and_b32_e32 v35, 63, v178
	v_lshrrev_b32_e32 v36, 6, v178
	v_and_b32_e32 v37, 15, v35
	v_lshrrev_b32_e32 v38, 4, v35
	s_nop 0
	v_readfirstlane_b32 s0, v36
	s_lshl_b32 s34, s34, 6
	s_lshl_b32 s0, s0, 4
	s_add_u32 s34, s34, s0
	s_and_b32 s1, s13, 3
	s_add_u32 s0, s15, s34
	v_add_u32_e32 v39, s0, v37
	v_and_b32_e32 v39, 0xfff, v39
	v_cmp_ne_u32_e32 vcc, 0, v39
	s_nop 1
	v_cndmask_b32_e64 v5, 0, -1, vcc
	s_movk_i32 s0, 0x1b00
	v_mul_lo_u32 v0, v37, s0
	v_lshlrev_b32_e32 v1, 4, v38
	v_lshlrev_b32_e32 v33, 5, v38
	s_lshl_b32 s0, s1, 8
	v_lshl_add_u32 v2, v38, 3, v0
	v_add_u32_e32 v2, s0, v2
	v_add_u32_e32 v4, v0, v1
	s_lshl_b32 s0, s1, 9
	v_add_u32_e32 v1, s0, v1
	v_lshlrev_b32_e32 v39, 7, v37
	s_lshl_b32 s0, s1, 14
	v_lshl_add_u32 v6, v38, 4, v39
	v_add_u32_e32 v6, s0, v6
	v_lshlrev_b32_e32 v39, 6, v37
	s_lshl_b32 s0, s1, 13
	v_lshl_add_u32 v7, v38, 4, v39
	v_add_u32_e32 v7, s0, v7
	v_lshlrev_b32_e32 v39, 10, v37
	s_lshl_b32 s0, s1, 8
	v_lshl_add_u32 v8, v38, 3, v39
	v_add_u32_e32 v8, s0, v8
	s_add_u32 s0, s15, s34
	s_lshl_b32 s0, s0, 10
	v_add_u32_e32 v8, s0, v8
	s_movk_i32 s0, 0x3e00
	v_mul_lo_u32 v36, v36, s0
	s_movk_i32 s0, 0x90
	v_mul_lo_u32 v39, v37, s0
	v_add_u32_e32 v9, v36, v39
	v_lshl_add_u32 v9, v38, 3, v9
	v_lshrrev_b32_e32 v39, 3, v35
	v_and_b32_e32 v35, 7, v35
	v_mul_lo_u32 v10, v39, s0
	v_add_u32_e32 v10, v36, v10
	v_lshl_add_u32 v10, v35, 4, v10
	v_lshlrev_b32_e32 v11, 10, v39
	v_lshl_add_u32 v11, v35, 4, v11
	s_lshl_b32 s0, s1, 8
	v_add_u32_e32 v11, s0, v11
	s_lshl_b32 s0, s34, 10
	v_add_u32_e32 v11, s0, v11
	v_add_u32_e32 v32, 0x2000, v11
	v_readlane_b32 s0, v233, 62
	v_readlane_b32 s1, v233, 63
	s_nop 4
	s_load_dwordx4 s[60:63], s[0:1], 0x40
	s_load_dwordx2 s[50:51], s[0:1], 0x50
	s_load_dwordx2 s[52:53], s[0:1], 0x60
	s_load_dwordx2 s[54:55], s[0:1], 0x70
	s_load_dwordx4 s[56:59], s[0:1], 0x80
	v_readlane_b32 s32, v234, 33
	s_mul_i32 s0, s34, 0x1b00
	s_add_u32 s40, s24, 0xa247000
	s_addc_u32 s41, s25, 0
	s_add_u32 s40, s40, s0
	s_addc_u32 s41, s41, 0
	s_sub_u32 s42, s40, 0x1b00
	s_subb_u32 s43, s41, 0
	s_sub_u32 s32, s32, 1
	s_waitcnt lgkmcnt(0)
	s_mul_i32 s0, s32, 0x1a00
	s_add_u32 s60, s60, s0
	s_addc_u32 s61, s61, 0
	s_add_u32 s46, s60, 0x800
	s_addc_u32 s47, s61, 0
	s_add_u32 s60, s60, 0x1800
	s_addc_u32 s61, s61, 0
	s_lshl_b32 s0, s32, 11
	s_add_u32 s50, s50, s0
	s_addc_u32 s51, s51, 0
	s_add_u32 s52, s52, s0
	s_addc_u32 s53, s53, 0
	s_add_u32 s56, s56, s0
	s_addc_u32 s57, s57, 0
	s_add_u32 s58, s58, s0
	s_addc_u32 s59, s59, 0
	s_max_i32 s1, s32, 1
	s_sub_u32 s1, s1, 1
	s_lshl_b32 s0, s1, 11
	s_add_u32 s54, s54, s0
	s_addc_u32 s55, s55, 0
	s_lshl_b32 s0, s1, 7
	s_add_u32 s62, s62, s0
	s_addc_u32 s63, s63, 0
	global_load_dwordx4 v[40:43], v4, s[40:41] offset:3072
	global_load_dwordx4 v[44:47], v4, s[42:43] offset:3072
	global_load_dwordx4 v[56:59], v4, s[40:41] offset:3136
	global_load_dwordx4 v[60:63], v4, s[42:43] offset:3136
	global_load_dwordx4 v[72:75], v4, s[40:41] offset:3200
	global_load_dwordx4 v[76:79], v4, s[42:43] offset:3200
	global_load_dwordx4 v[88:91], v4, s[40:41] offset:3264
	global_load_dwordx4 v[92:95], v4, s[42:43] offset:3264
	s_mov_b32 exec_lo, 0x10001
	s_mov_b32 exec_hi, 0x10001
	global_load_dwordx4 v[48:51], v33, s[60:61] offset:0
	global_load_dwordx4 v[52:55], v33, s[60:61] offset:16
	global_load_dwordx4 v[64:67], v33, s[60:61] offset:128
	global_load_dwordx4 v[68:71], v33, s[60:61] offset:144
	global_load_dwordx4 v[80:83], v33, s[60:61] offset:256
	global_load_dwordx4 v[84:87], v33, s[60:61] offset:272
	global_load_dwordx4 v[96:99], v33, s[60:61] offset:384
	global_load_dwordx4 v[100:103], v33, s[60:61] offset:400
	s_mov_b64 exec, -1
	s_cmp_eq_u32 s32, 0
	s_cbranch_scc1 .Lprep2_noV
	s_add_u32 s0, s40, 0x1000
	s_addc_u32 s1, s41, 0
	global_load_dwordx4 v[104:107], v4, s[0:1] offset:2624
	s_add_u32 s0, s42, 0x1000
	s_addc_u32 s1, s43, 0
	global_load_dwordx4 v[108:111], v4, s[0:1] offset:2624
	s_mov_b32 exec_lo, 0x10001
	s_mov_b32 exec_hi, 0x10001
	global_load_dwordx4 v[112:115], v33, s[62:63]
	global_load_dwordx4 v[116:119], v33, s[62:63] offset:16
	s_mov_b64 exec, -1
.Lprep2_noV:
	s_lshl_b32 s0, s32, 16
	s_add_u32 s60, s24, 0x2ba7000
	s_addc_u32 s61, s25, 0
	s_add_u32 s60, s60, s0
	s_addc_u32 s61, s61, 0
	s_lshl_b32 s0, s32, 15
	s_add_u32 s100, s24, 0x2c27000
	s_addc_u32 s101, s25, 0
	s_add_u32 s100, s100, s0
	s_addc_u32 s101, s101, 0
	s_add_u32 s0, s24, 0x2c47000
	s_addc_u32 s1, s25, 0
	s_waitcnt vmcnt(0)
	v_mov_b32_dpp v48, v48 row_newbcast:0 row_mask:0xf bank_mask:0xf
	v_mov_b32_dpp v49, v49 row_newbcast:0 row_mask:0xf bank_mask:0xf
	v_mov_b32_dpp v50, v50 row_newbcast:0 row_mask:0xf bank_mask:0xf
	v_mov_b32_dpp v51, v51 row_newbcast:0 row_mask:0xf bank_mask:0xf
	v_mov_b32_dpp v52, v52 row_newbcast:0 row_mask:0xf bank_mask:0xf
	v_mov_b32_dpp v53, v53 row_newbcast:0 row_mask:0xf bank_mask:0xf
	v_mov_b32_dpp v54, v54 row_newbcast:0 row_mask:0xf bank_mask:0xf
	v_mov_b32_dpp v55, v55 row_newbcast:0 row_mask:0xf bank_mask:0xf
	v_and_b32_e32 v44, v5, v44
	v_lshlrev_b32_e32 v164, 16, v40
	v_and_b32_e32 v165, 0xffff0000, v40
	v_lshlrev_b32_e32 v166, 16, v44
	v_and_b32_e32 v167, 0xffff0000, v44
	v_sub_f32_e32 v166, v166, v164
	v_sub_f32_e32 v167, v167, v165
	v_fmac_f32_e32 v164, v48, v166
	v_fmac_f32_e32 v165, v49, v167
	v_add_f32_e32 v164, v164, v164
	v_mul_f32_e32 v164, 0x3fb8aa3b, v164
	v_exp_f32_e32 v164, v164
	s_nop 0
	v_add_f32_e32 v164, 1.0, v164
	v_rcp_f32_e32 v164, v164
	s_nop 0
	v_fma_f32 v164, v164, -2.0, 1.0
	v_add_f32_e32 v165, v165, v165
	v_mul_f32_e32 v165, 0x3fb8aa3b, v165
	v_exp_f32_e32 v165, v165
	s_nop 0
	v_add_f32_e32 v165, 1.0, v165
	v_rcp_f32_e32 v165, v165
	s_nop 0
	v_fma_f32 v165, v165, -2.0, 1.0
	v_cvt_pk_bf16_f32 v12, v164, v165
	v_and_b32_e32 v45, v5, v45
	v_lshlrev_b32_e32 v164, 16, v41
	v_and_b32_e32 v165, 0xffff0000, v41
	v_lshlrev_b32_e32 v166, 16, v45
	v_and_b32_e32 v167, 0xffff0000, v45
	v_sub_f32_e32 v166, v166, v164
	v_sub_f32_e32 v167, v167, v165
	v_fmac_f32_e32 v164, v50, v166
	v_fmac_f32_e32 v165, v51, v167
	v_add_f32_e32 v164, v164, v164
	v_mul_f32_e32 v164, 0x3fb8aa3b, v164
	v_exp_f32_e32 v164, v164
	s_nop 0
	v_add_f32_e32 v164, 1.0, v164
	v_rcp_f32_e32 v164, v164
	s_nop 0
	v_fma_f32 v164, v164, -2.0, 1.0
	v_add_f32_e32 v165, v165, v165
	v_mul_f32_e32 v165, 0x3fb8aa3b, v165
	v_exp_f32_e32 v165, v165
	s_nop 0
	v_add_f32_e32 v165, 1.0, v165
	v_rcp_f32_e32 v165, v165
	s_nop 0
	v_fma_f32 v165, v165, -2.0, 1.0
	v_cvt_pk_bf16_f32 v13, v164, v165
	v_and_b32_e32 v46, v5, v46
	v_lshlrev_b32_e32 v164, 16, v42
	v_and_b32_e32 v165, 0xffff0000, v42
	v_lshlrev_b32_e32 v166, 16, v46
	v_and_b32_e32 v167, 0xffff0000, v46
	v_sub_f32_e32 v166, v166, v164
	v_sub_f32_e32 v167, v167, v165
	v_fmac_f32_e32 v164, v52, v166
	v_fmac_f32_e32 v165, v53, v167
	v_add_f32_e32 v164, v164, v164
	v_mul_f32_e32 v164, 0x3fb8aa3b, v164
	v_exp_f32_e32 v164, v164
	s_nop 0
	v_add_f32_e32 v164, 1.0, v164
	v_rcp_f32_e32 v164, v164
	s_nop 0
	v_fma_f32 v164, v164, -2.0, 1.0
	v_add_f32_e32 v165, v165, v165
	v_mul_f32_e32 v165, 0x3fb8aa3b, v165
	v_exp_f32_e32 v165, v165
	s_nop 0
	v_add_f32_e32 v165, 1.0, v165
	v_rcp_f32_e32 v165, v165
	s_nop 0
	v_fma_f32 v165, v165, -2.0, 1.0
	v_cvt_pk_bf16_f32 v14, v164, v165
	v_and_b32_e32 v47, v5, v47
	v_lshlrev_b32_e32 v164, 16, v43
	v_and_b32_e32 v165, 0xffff0000, v43
	v_lshlrev_b32_e32 v166, 16, v47
	v_and_b32_e32 v167, 0xffff0000, v47
	v_sub_f32_e32 v166, v166, v164
	v_sub_f32_e32 v167, v167, v165
	v_fmac_f32_e32 v164, v54, v166
	v_fmac_f32_e32 v165, v55, v167
	v_add_f32_e32 v164, v164, v164
	v_mul_f32_e32 v164, 0x3fb8aa3b, v164
	v_exp_f32_e32 v164, v164
	s_nop 0
	v_add_f32_e32 v164, 1.0, v164
	v_rcp_f32_e32 v164, v164
	s_nop 0
	v_fma_f32 v164, v164, -2.0, 1.0
	v_add_f32_e32 v165, v165, v165
	v_mul_f32_e32 v165, 0x3fb8aa3b, v165
	v_exp_f32_e32 v165, v165
	s_nop 0
	v_add_f32_e32 v165, 1.0, v165
	v_rcp_f32_e32 v165, v165
	s_nop 0
	v_fma_f32 v165, v165, -2.0, 1.0
	v_cvt_pk_bf16_f32 v15, v164, v165
	v_mov_b32_dpp v64, v64 row_newbcast:0 row_mask:0xf bank_mask:0xf
	v_mov_b32_dpp v65, v65 row_newbcast:0 row_mask:0xf bank_mask:0xf
	v_mov_b32_dpp v66, v66 row_newbcast:0 row_mask:0xf bank_mask:0xf
	v_mov_b32_dpp v67, v67 row_newbcast:0 row_mask:0xf bank_mask:0xf
	v_mov_b32_dpp v68, v68 row_newbcast:0 row_mask:0xf bank_mask:0xf
	v_mov_b32_dpp v69, v69 row_newbcast:0 row_mask:0xf bank_mask:0xf
	v_mov_b32_dpp v70, v70 row_newbcast:0 row_mask:0xf bank_mask:0xf
	v_mov_b32_dpp v71, v71 row_newbcast:0 row_mask:0xf bank_mask:0xf
	v_and_b32_e32 v60, v5, v60
	v_lshlrev_b32_e32 v164, 16, v56
	v_and_b32_e32 v165, 0xffff0000, v56
	v_lshlrev_b32_e32 v166, 16, v60
	v_and_b32_e32 v167, 0xffff0000, v60
	v_sub_f32_e32 v166, v166, v164
	v_sub_f32_e32 v167, v167, v165
	v_fmac_f32_e32 v164, v64, v166
	v_fmac_f32_e32 v165, v65, v167
	v_add_f32_e32 v164, v164, v164
	v_mul_f32_e32 v164, 0x3fb8aa3b, v164
	v_exp_f32_e32 v164, v164
	s_nop 0
	v_add_f32_e32 v164, 1.0, v164
	v_rcp_f32_e32 v164, v164
	s_nop 0
	v_fma_f32 v164, v164, -2.0, 1.0
	v_add_f32_e32 v165, v165, v165
	v_mul_f32_e32 v165, 0x3fb8aa3b, v165
	v_exp_f32_e32 v165, v165
	s_nop 0
	v_add_f32_e32 v165, 1.0, v165
	v_rcp_f32_e32 v165, v165
	s_nop 0
	v_fma_f32 v165, v165, -2.0, 1.0
	v_cvt_pk_bf16_f32 v16, v164, v165
	v_and_b32_e32 v61, v5, v61
	v_lshlrev_b32_e32 v164, 16, v57
	v_and_b32_e32 v165, 0xffff0000, v57
	v_lshlrev_b32_e32 v166, 16, v61
	v_and_b32_e32 v167, 0xffff0000, v61
	v_sub_f32_e32 v166, v166, v164
	v_sub_f32_e32 v167, v167, v165
	v_fmac_f32_e32 v164, v66, v166
	v_fmac_f32_e32 v165, v67, v167
	v_add_f32_e32 v164, v164, v164
	v_mul_f32_e32 v164, 0x3fb8aa3b, v164
	v_exp_f32_e32 v164, v164
	s_nop 0
	v_add_f32_e32 v164, 1.0, v164
	v_rcp_f32_e32 v164, v164
	s_nop 0
	v_fma_f32 v164, v164, -2.0, 1.0
	v_add_f32_e32 v165, v165, v165
	v_mul_f32_e32 v165, 0x3fb8aa3b, v165
	v_exp_f32_e32 v165, v165
	s_nop 0
	v_add_f32_e32 v165, 1.0, v165
	v_rcp_f32_e32 v165, v165
	s_nop 0
	v_fma_f32 v165, v165, -2.0, 1.0
	v_cvt_pk_bf16_f32 v17, v164, v165
	v_and_b32_e32 v62, v5, v62
	v_lshlrev_b32_e32 v164, 16, v58
	v_and_b32_e32 v165, 0xffff0000, v58
	v_lshlrev_b32_e32 v166, 16, v62
	v_and_b32_e32 v167, 0xffff0000, v62
	v_sub_f32_e32 v166, v166, v164
	v_sub_f32_e32 v167, v167, v165
	v_fmac_f32_e32 v164, v68, v166
	v_fmac_f32_e32 v165, v69, v167
	v_add_f32_e32 v164, v164, v164
	v_mul_f32_e32 v164, 0x3fb8aa3b, v164
	v_exp_f32_e32 v164, v164
	s_nop 0
	v_add_f32_e32 v164, 1.0, v164
	v_rcp_f32_e32 v164, v164
	s_nop 0
	v_fma_f32 v164, v164, -2.0, 1.0
	v_add_f32_e32 v165, v165, v165
	v_mul_f32_e32 v165, 0x3fb8aa3b, v165
	v_exp_f32_e32 v165, v165
	s_nop 0
	v_add_f32_e32 v165, 1.0, v165
	v_rcp_f32_e32 v165, v165
	s_nop 0
	v_fma_f32 v165, v165, -2.0, 1.0
	v_cvt_pk_bf16_f32 v18, v164, v165
	v_and_b32_e32 v63, v5, v63
	v_lshlrev_b32_e32 v164, 16, v59
	v_and_b32_e32 v165, 0xffff0000, v59
	v_lshlrev_b32_e32 v166, 16, v63
	v_and_b32_e32 v167, 0xffff0000, v63
	v_sub_f32_e32 v166, v166, v164
	v_sub_f32_e32 v167, v167, v165
	v_fmac_f32_e32 v164, v70, v166
	v_fmac_f32_e32 v165, v71, v167
	v_add_f32_e32 v164, v164, v164
	v_mul_f32_e32 v164, 0x3fb8aa3b, v164
	v_exp_f32_e32 v164, v164
	s_nop 0
	v_add_f32_e32 v164, 1.0, v164
	v_rcp_f32_e32 v164, v164
	s_nop 0
	v_fma_f32 v164, v164, -2.0, 1.0
	v_add_f32_e32 v165, v165, v165
	v_mul_f32_e32 v165, 0x3fb8aa3b, v165
	v_exp_f32_e32 v165, v165
	s_nop 0
	v_add_f32_e32 v165, 1.0, v165
	v_rcp_f32_e32 v165, v165
	s_nop 0
	v_fma_f32 v165, v165, -2.0, 1.0
	v_cvt_pk_bf16_f32 v19, v164, v165
	v_mov_b32_dpp v80, v80 row_newbcast:0 row_mask:0xf bank_mask:0xf
	v_mov_b32_dpp v81, v81 row_newbcast:0 row_mask:0xf bank_mask:0xf
	v_mov_b32_dpp v82, v82 row_newbcast:0 row_mask:0xf bank_mask:0xf
	v_mov_b32_dpp v83, v83 row_newbcast:0 row_mask:0xf bank_mask:0xf
	v_mov_b32_dpp v84, v84 row_newbcast:0 row_mask:0xf bank_mask:0xf
	v_mov_b32_dpp v85, v85 row_newbcast:0 row_mask:0xf bank_mask:0xf
	v_mov_b32_dpp v86, v86 row_newbcast:0 row_mask:0xf bank_mask:0xf
	v_mov_b32_dpp v87, v87 row_newbcast:0 row_mask:0xf bank_mask:0xf
	v_and_b32_e32 v76, v5, v76
	v_lshlrev_b32_e32 v164, 16, v72
	v_and_b32_e32 v165, 0xffff0000, v72
	v_lshlrev_b32_e32 v166, 16, v76
	v_and_b32_e32 v167, 0xffff0000, v76
	v_sub_f32_e32 v166, v166, v164
	v_sub_f32_e32 v167, v167, v165
	v_fmac_f32_e32 v164, v80, v166
	v_fmac_f32_e32 v165, v81, v167
	v_cvt_pk_bf16_f32 v20, v164, v165
	v_and_b32_e32 v77, v5, v77
	v_lshlrev_b32_e32 v164, 16, v73
	v_and_b32_e32 v165, 0xffff0000, v73
	v_lshlrev_b32_e32 v166, 16, v77
	v_and_b32_e32 v167, 0xffff0000, v77
	v_sub_f32_e32 v166, v166, v164
	v_sub_f32_e32 v167, v167, v165
	v_fmac_f32_e32 v164, v82, v166
	v_fmac_f32_e32 v165, v83, v167
	v_cvt_pk_bf16_f32 v21, v164, v165
	v_and_b32_e32 v78, v5, v78
	v_lshlrev_b32_e32 v164, 16, v74
	v_and_b32_e32 v165, 0xffff0000, v74
	v_lshlrev_b32_e32 v166, 16, v78
	v_and_b32_e32 v167, 0xffff0000, v78
	v_sub_f32_e32 v166, v166, v164
	v_sub_f32_e32 v167, v167, v165
	v_fmac_f32_e32 v164, v84, v166
	v_fmac_f32_e32 v165, v85, v167
	v_cvt_pk_bf16_f32 v22, v164, v165
	v_and_b32_e32 v79, v5, v79
	v_lshlrev_b32_e32 v164, 16, v75
	v_and_b32_e32 v165, 0xffff0000, v75
	v_lshlrev_b32_e32 v166, 16, v79
	v_and_b32_e32 v167, 0xffff0000, v79
	v_sub_f32_e32 v166, v166, v164
	v_sub_f32_e32 v167, v167, v165
	v_fmac_f32_e32 v164, v86, v166
	v_fmac_f32_e32 v165, v87, v167
	v_cvt_pk_bf16_f32 v23, v164, v165
	v_mov_b32_dpp v96, v96 row_newbcast:0 row_mask:0xf bank_mask:0xf
	v_mov_b32_dpp v97, v97 row_newbcast:0 row_mask:0xf bank_mask:0xf
	v_mov_b32_dpp v98, v98 row_newbcast:0 row_mask:0xf bank_mask:0xf
	v_mov_b32_dpp v99, v99 row_newbcast:0 row_mask:0xf bank_mask:0xf
	v_mov_b32_dpp v100, v100 row_newbcast:0 row_mask:0xf bank_mask:0xf
	v_mov_b32_dpp v101, v101 row_newbcast:0 row_mask:0xf bank_mask:0xf
	v_mov_b32_dpp v102, v102 row_newbcast:0 row_mask:0xf bank_mask:0xf
	v_mov_b32_dpp v103, v103 row_newbcast:0 row_mask:0xf bank_mask:0xf
	v_and_b32_e32 v92, v5, v92
	v_lshlrev_b32_e32 v164, 16, v88
	v_and_b32_e32 v165, 0xffff0000, v88
	v_lshlrev_b32_e32 v166, 16, v92
	v_and_b32_e32 v167, 0xffff0000, v92
	v_sub_f32_e32 v166, v166, v164
	v_sub_f32_e32 v167, v167, v165
	v_fmac_f32_e32 v164, v96, v166
	v_fmac_f32_e32 v165, v97, v167
	v_cvt_pk_bf16_f32 v24, v164, v165
	v_and_b32_e32 v93, v5, v93
	v_lshlrev_b32_e32 v164, 16, v89
	v_and_b32_e32 v165, 0xffff0000, v89
	v_lshlrev_b32_e32 v166, 16, v93
	v_and_b32_e32 v167, 0xffff0000, v93
	v_sub_f32_e32 v166, v166, v164
	v_sub_f32_e32 v167, v167, v165
	v_fmac_f32_e32 v164, v98, v166
	v_fmac_f32_e32 v165, v99, v167
	v_cvt_pk_bf16_f32 v25, v164, v165
	v_and_b32_e32 v94, v5, v94
	v_lshlrev_b32_e32 v164, 16, v90
	v_and_b32_e32 v165, 0xffff0000, v90
	v_lshlrev_b32_e32 v166, 16, v94
	v_and_b32_e32 v167, 0xffff0000, v94
	v_sub_f32_e32 v166, v166, v164
	v_sub_f32_e32 v167, v167, v165
	v_fmac_f32_e32 v164, v100, v166
	v_fmac_f32_e32 v165, v101, v167
	v_cvt_pk_bf16_f32 v26, v164, v165
	v_and_b32_e32 v95, v5, v95
	v_lshlrev_b32_e32 v164, 16, v91
	v_and_b32_e32 v165, 0xffff0000, v91
	v_lshlrev_b32_e32 v166, 16, v95
	v_and_b32_e32 v167, 0xffff0000, v95
	v_sub_f32_e32 v166, v166, v164
	v_sub_f32_e32 v167, v167, v165
	v_fmac_f32_e32 v164, v102, v166
	v_fmac_f32_e32 v165, v103, v167
	v_cvt_pk_bf16_f32 v27, v164, v165
	s_cmp_eq_u32 s32, 0
	s_cbranch_scc1 .Lprep2_bvz
	v_mov_b32_dpp v112, v112 row_newbcast:0 row_mask:0xf bank_mask:0xf
	v_mov_b32_dpp v113, v113 row_newbcast:0 row_mask:0xf bank_mask:0xf
	v_mov_b32_dpp v114, v114 row_newbcast:0 row_mask:0xf bank_mask:0xf
	v_mov_b32_dpp v115, v115 row_newbcast:0 row_mask:0xf bank_mask:0xf
	v_mov_b32_dpp v116, v116 row_newbcast:0 row_mask:0xf bank_mask:0xf
	v_mov_b32_dpp v117, v117 row_newbcast:0 row_mask:0xf bank_mask:0xf
	v_mov_b32_dpp v118, v118 row_newbcast:0 row_mask:0xf bank_mask:0xf
	v_mov_b32_dpp v119, v119 row_newbcast:0 row_mask:0xf bank_mask:0xf
	v_and_b32_e32 v108, v5, v108
	v_lshlrev_b32_e32 v164, 16, v104
	v_and_b32_e32 v165, 0xffff0000, v104
	v_lshlrev_b32_e32 v166, 16, v108
	v_and_b32_e32 v167, 0xffff0000, v108
	v_sub_f32_e32 v166, v166, v164
	v_sub_f32_e32 v167, v167, v165
	v_fmac_f32_e32 v164, v112, v166
	v_fmac_f32_e32 v165, v113, v167
	v_cvt_pk_bf16_f32 v28, v164, v165
	v_and_b32_e32 v109, v5, v109
	v_lshlrev_b32_e32 v164, 16, v105
	v_and_b32_e32 v165, 0xffff0000, v105
	v_lshlrev_b32_e32 v166, 16, v109
	v_and_b32_e32 v167, 0xffff0000, v109
	v_sub_f32_e32 v166, v166, v164
	v_sub_f32_e32 v167, v167, v165
	v_fmac_f32_e32 v164, v114, v166
	v_fmac_f32_e32 v165, v115, v167
	v_cvt_pk_bf16_f32 v29, v164, v165
	v_and_b32_e32 v110, v5, v110
	v_lshlrev_b32_e32 v164, 16, v106
	v_and_b32_e32 v165, 0xffff0000, v106
	v_lshlrev_b32_e32 v166, 16, v110
	v_and_b32_e32 v167, 0xffff0000, v110
	v_sub_f32_e32 v166, v166, v164
	v_sub_f32_e32 v167, v167, v165
	v_fmac_f32_e32 v164, v116, v166
	v_fmac_f32_e32 v165, v117, v167
	v_cvt_pk_bf16_f32 v30, v164, v165
	v_and_b32_e32 v111, v5, v111
	v_lshlrev_b32_e32 v164, 16, v107
	v_and_b32_e32 v165, 0xffff0000, v107
	v_lshlrev_b32_e32 v166, 16, v111
	v_and_b32_e32 v167, 0xffff0000, v111
	v_sub_f32_e32 v166, v166, v164
	v_sub_f32_e32 v167, v167, v165
	v_fmac_f32_e32 v164, v118, v166
	v_fmac_f32_e32 v165, v119, v167
	v_cvt_pk_bf16_f32 v31, v164, v165
	s_branch .Lprep2_bvd
.Lprep2_bvz:
	v_mov_b32_e32 v28, 0
	v_mov_b32_e32 v29, 0
	v_mov_b32_e32 v30, 0
	v_mov_b32_e32 v31, 0
.Lprep2_bvd:
	v_mov_b32_e32 v176, v6
	v_add_u32_e32 v177, 0x1000, v6
	v_mov_b32_e32 v181, v7
	v_add_u32_e32 v182, 0x40000, v6
	v_add_u32_e32 v183, 0x41000, v6
	global_load_dwordx2 v[40:41], v2, s[40:41] offset:1024
	global_load_dwordx2 v[42:43], v2, s[42:43] offset:1024
	global_load_dwordx2 v[52:53], v2, s[40:41] offset:1056
	global_load_dwordx2 v[54:55], v2, s[42:43] offset:1056
	global_load_dwordx2 v[64:65], v2, s[40:41] offset:1088
	global_load_dwordx2 v[66:67], v2, s[42:43] offset:1088
	global_load_dwordx2 v[76:77], v2, s[40:41] offset:1120
	global_load_dwordx2 v[78:79], v2, s[42:43] offset:1120
	s_mov_b32 exec_lo, 0x10001
	s_mov_b32 exec_hi, 0x10001
	global_load_dwordx4 v[44:47], v1, s[46:47] offset:0
	global_load_dwordx4 v[48:51], v1, s[56:57] offset:0
	global_load_dwordx4 v[56:59], v1, s[46:47] offset:64
	global_load_dwordx4 v[60:63], v1, s[56:57] offset:64
	global_load_dwordx4 v[68:71], v1, s[46:47] offset:128
	global_load_dwordx4 v[72:75], v1, s[56:57] offset:128
	global_load_dwordx4 v[80:83], v1, s[46:47] offset:192
	global_load_dwordx4 v[84:87], v1, s[56:57] offset:192
	s_mov_b64 exec, -1
	global_load_dwordx2 v[88:89], v2, s[40:41] offset:0
	global_load_dwordx2 v[90:91], v2, s[42:43] offset:0
	global_load_dwordx2 v[96:97], v2, s[40:41] offset:2048
	global_load_dwordx2 v[98:99], v2, s[42:43] offset:2048
	global_load_dwordx4 v[104:107], v176, s[60:61] offset:0
	global_load_dwordx4 v[108:111], v176, s[60:61] offset:64
	global_load_dwordx4 v[112:115], v182, s[60:61] offset:0
	global_load_dwordx4 v[116:119], v182, s[60:61] offset:64
	global_load_dwordx4 v[120:123], v181, s[100:101] offset:0
	global_load_dwordx2 v[140:141], v8, s[0:1] offset:0
	s_mov_b32 exec_lo, 0x10001
	s_mov_b32 exec_hi, 0x10001
	global_load_dwordx4 v[92:95], v1, s[46:47] offset:-2048
	global_load_dwordx4 v[100:103], v1, s[46:47] offset:2048
	global_load_dwordx4 v[124:127], v1, s[50:51] offset:0
	global_load_dwordx4 v[128:131], v1, s[52:53] offset:0
	global_load_dwordx4 v[132:135], v1, s[58:59] offset:0
	global_load_dwordx4 v[136:139], v1, s[54:55] offset:0
	s_mov_b64 exec, -1
	s_waitcnt vmcnt(16)
	v_mov_b32_dpp v44, v44 row_newbcast:0 row_mask:0xf bank_mask:0xf
	v_mov_b32_dpp v45, v45 row_newbcast:0 row_mask:0xf bank_mask:0xf
	v_mov_b32_dpp v46, v46 row_newbcast:0 row_mask:0xf bank_mask:0xf
	v_mov_b32_dpp v47, v47 row_newbcast:0 row_mask:0xf bank_mask:0xf
	v_mov_b32_dpp v48, v48 row_newbcast:0 row_mask:0xf bank_mask:0xf
	v_mov_b32_dpp v49, v49 row_newbcast:0 row_mask:0xf bank_mask:0xf
	v_mov_b32_dpp v50, v50 row_newbcast:0 row_mask:0xf bank_mask:0xf
	v_mov_b32_dpp v51, v51 row_newbcast:0 row_mask:0xf bank_mask:0xf
	v_and_b32_e32 v42, v5, v42
	v_and_b32_e32 v43, v5, v43
	v_lshlrev_b32_e32 v204, 16, v40
	v_and_b32_e32 v205, 0xffff0000, v40
	v_lshlrev_b32_e32 v220, 16, v42
	v_and_b32_e32 v221, 0xffff0000, v42
	v_sub_f32_e32 v220, v220, v204
	v_sub_f32_e32 v221, v221, v205
	v_fmac_f32_e32 v204, v44, v220
	v_fmac_f32_e32 v205, v45, v221
	v_lshlrev_b32_e32 v206, 16, v41
	v_and_b32_e32 v207, 0xffff0000, v41
	v_lshlrev_b32_e32 v220, 16, v43
	v_and_b32_e32 v221, 0xffff0000, v43
	v_sub_f32_e32 v220, v220, v206
	v_sub_f32_e32 v221, v221, v207
	v_fmac_f32_e32 v206, v46, v220
	v_fmac_f32_e32 v207, v47, v221
	v_mul_f32_e32 v148, v204, v48
	v_mul_f32_e32 v149, v205, v49
	v_mul_f32_e32 v150, v206, v50
	v_mul_f32_e32 v151, v207, v51
	v_mul_f32_e32 v223, v148, v148
	v_fma_f32 v223, v149, v149, v223
	v_fma_f32 v223, v150, v150, v223
	v_fma_f32 v223, v151, v151, v223
	v_mov_b32_e32 v222, v223
	v_mov_b32_dpp v56, v56 row_newbcast:0 row_mask:0xf bank_mask:0xf
	v_mov_b32_dpp v57, v57 row_newbcast:0 row_mask:0xf bank_mask:0xf
	v_mov_b32_dpp v58, v58 row_newbcast:0 row_mask:0xf bank_mask:0xf
	v_mov_b32_dpp v59, v59 row_newbcast:0 row_mask:0xf bank_mask:0xf
	v_mov_b32_dpp v60, v60 row_newbcast:0 row_mask:0xf bank_mask:0xf
	v_mov_b32_dpp v61, v61 row_newbcast:0 row_mask:0xf bank_mask:0xf
	v_mov_b32_dpp v62, v62 row_newbcast:0 row_mask:0xf bank_mask:0xf
	v_mov_b32_dpp v63, v63 row_newbcast:0 row_mask:0xf bank_mask:0xf
	v_and_b32_e32 v54, v5, v54
	v_and_b32_e32 v55, v5, v55
	v_lshlrev_b32_e32 v208, 16, v52
	v_and_b32_e32 v209, 0xffff0000, v52
	v_lshlrev_b32_e32 v220, 16, v54
	v_and_b32_e32 v221, 0xffff0000, v54
	v_sub_f32_e32 v220, v220, v208
	v_sub_f32_e32 v221, v221, v209
	v_fmac_f32_e32 v208, v56, v220
	v_fmac_f32_e32 v209, v57, v221
	v_lshlrev_b32_e32 v210, 16, v53
	v_and_b32_e32 v211, 0xffff0000, v53
	v_lshlrev_b32_e32 v220, 16, v55
	v_and_b32_e32 v221, 0xffff0000, v55
	v_sub_f32_e32 v220, v220, v210
	v_sub_f32_e32 v221, v221, v211
	v_fmac_f32_e32 v210, v58, v220
	v_fmac_f32_e32 v211, v59, v221
	v_mul_f32_e32 v152, v208, v60
	v_mul_f32_e32 v153, v209, v61
	v_mul_f32_e32 v154, v210, v62
	v_mul_f32_e32 v155, v211, v63
	v_mul_f32_e32 v223, v152, v152
	v_fma_f32 v223, v153, v153, v223
	v_fma_f32 v223, v154, v154, v223
	v_fma_f32 v223, v155, v155, v223
	v_add_f32_e32 v222, v222, v223
	v_mov_b32_dpp v68, v68 row_newbcast:0 row_mask:0xf bank_mask:0xf
	v_mov_b32_dpp v69, v69 row_newbcast:0 row_mask:0xf bank_mask:0xf
	v_mov_b32_dpp v70, v70 row_newbcast:0 row_mask:0xf bank_mask:0xf
	v_mov_b32_dpp v71, v71 row_newbcast:0 row_mask:0xf bank_mask:0xf
	v_mov_b32_dpp v72, v72 row_newbcast:0 row_mask:0xf bank_mask:0xf
	v_mov_b32_dpp v73, v73 row_newbcast:0 row_mask:0xf bank_mask:0xf
	v_mov_b32_dpp v74, v74 row_newbcast:0 row_mask:0xf bank_mask:0xf
	v_mov_b32_dpp v75, v75 row_newbcast:0 row_mask:0xf bank_mask:0xf
	v_and_b32_e32 v66, v5, v66
	v_and_b32_e32 v67, v5, v67
	v_lshlrev_b32_e32 v212, 16, v64
	v_and_b32_e32 v213, 0xffff0000, v64
	v_lshlrev_b32_e32 v220, 16, v66
	v_and_b32_e32 v221, 0xffff0000, v66
	v_sub_f32_e32 v220, v220, v212
	v_sub_f32_e32 v221, v221, v213
	v_fmac_f32_e32 v212, v68, v220
	v_fmac_f32_e32 v213, v69, v221
	v_lshlrev_b32_e32 v214, 16, v65
	v_and_b32_e32 v215, 0xffff0000, v65
	v_lshlrev_b32_e32 v220, 16, v67
	v_and_b32_e32 v221, 0xffff0000, v67
	v_sub_f32_e32 v220, v220, v214
	v_sub_f32_e32 v221, v221, v215
	v_fmac_f32_e32 v214, v70, v220
	v_fmac_f32_e32 v215, v71, v221
	v_mul_f32_e32 v156, v212, v72
	v_mul_f32_e32 v157, v213, v73
	v_mul_f32_e32 v158, v214, v74
	v_mul_f32_e32 v159, v215, v75
	v_mul_f32_e32 v223, v156, v156
	v_fma_f32 v223, v157, v157, v223
	v_fma_f32 v223, v158, v158, v223
	v_fma_f32 v223, v159, v159, v223
	v_add_f32_e32 v222, v222, v223
	v_mov_b32_dpp v80, v80 row_newbcast:0 row_mask:0xf bank_mask:0xf
	v_mov_b32_dpp v81, v81 row_newbcast:0 row_mask:0xf bank_mask:0xf
	v_mov_b32_dpp v82, v82 row_newbcast:0 row_mask:0xf bank_mask:0xf
	v_mov_b32_dpp v83, v83 row_newbcast:0 row_mask:0xf bank_mask:0xf
	v_mov_b32_dpp v84, v84 row_newbcast:0 row_mask:0xf bank_mask:0xf
	v_mov_b32_dpp v85, v85 row_newbcast:0 row_mask:0xf bank_mask:0xf
	v_mov_b32_dpp v86, v86 row_newbcast:0 row_mask:0xf bank_mask:0xf
	v_mov_b32_dpp v87, v87 row_newbcast:0 row_mask:0xf bank_mask:0xf
	v_and_b32_e32 v78, v5, v78
	v_and_b32_e32 v79, v5, v79
	v_lshlrev_b32_e32 v216, 16, v76
	v_and_b32_e32 v217, 0xffff0000, v76
	v_lshlrev_b32_e32 v220, 16, v78
	v_and_b32_e32 v221, 0xffff0000, v78
	v_sub_f32_e32 v220, v220, v216
	v_sub_f32_e32 v221, v221, v217
	v_fmac_f32_e32 v216, v80, v220
	v_fmac_f32_e32 v217, v81, v221
	v_lshlrev_b32_e32 v218, 16, v77
	v_and_b32_e32 v219, 0xffff0000, v77
	v_lshlrev_b32_e32 v220, 16, v79
	v_and_b32_e32 v221, 0xffff0000, v79
	v_sub_f32_e32 v220, v220, v218
	v_sub_f32_e32 v221, v221, v219
	v_fmac_f32_e32 v218, v82, v220
	v_fmac_f32_e32 v219, v83, v221
	v_mul_f32_e32 v160, v216, v84
	v_mul_f32_e32 v161, v217, v85
	v_mul_f32_e32 v162, v218, v86
	v_mul_f32_e32 v163, v219, v87
	v_mul_f32_e32 v223, v160, v160
	v_fma_f32 v223, v161, v161, v223
	v_fma_f32 v223, v162, v162, v223
	v_fma_f32 v223, v163, v163, v223
	v_add_f32_e32 v222, v222, v223
	v_mov_b32_e32 v223, v222
	s_nop 1
	v_permlane16_swap_b32_e32 v222, v223
	s_nop 1
	v_add_f32_e32 v222, v222, v223
	v_mov_b32_e32 v223, v222
	s_nop 1
	v_permlane32_swap_b32_e32 v222, v223
	s_nop 1
	v_add_f32_e32 v222, v222, v223
	s_mov_b32 s34, 0xf800000
	v_cmp_gt_f32_e32 vcc, s34, v222
	v_mul_f32_e32 v220, 0x4f800000, v222
	s_nop 0
	v_cndmask_b32_e32 v222, v222, v220, vcc
	v_sqrt_f32_e32 v224, v222
	s_nop 0
	v_add_u32_e32 v225, -1, v224
	v_fma_f32 v226, -v225, v224, v222
	v_cmp_ge_f32_e64 s[62:63], 0, v226
	v_add_u32_e32 v227, 1, v224
	s_nop 0
	v_cndmask_b32_e64 v225, v224, v225, s[62:63]
	v_fma_f32 v226, -v227, v224, v222
	v_cmp_lt_f32_e64 s[62:63], 0, v226
	s_nop 1
	v_cndmask_b32_e64 v224, v225, v227, s[62:63]
	v_mul_f32_e32 v220, 0x37800000, v224
	v_cndmask_b32_e32 v224, v224, v220, vcc
	v_cmp_class_f32_e32 vcc, v222, v193
	s_nop 1
	v_cndmask_b32_e32 v222, v224, v222, vcc
	v_max_f32_e32 v222, 0x2b8cbccc, v222
	v_div_scale_f32 v224, s[62:63], v222, v222, 1.0
	v_rcp_f32_e32 v225, v224
	s_nop 0
	v_fma_f32 v226, -v224, v225, 1.0
	v_fmac_f32_e32 v225, v226, v225
	v_div_scale_f32 v227, vcc, 1.0, v222, 1.0
	v_mul_f32_e32 v220, v227, v225
	v_fma_f32 v221, -v224, v220, v227
	v_fmac_f32_e32 v220, v221, v225
	v_fma_f32 v224, -v224, v220, v227
	s_nop 1
	v_div_fmas_f32 v224, v224, v225, v220
	v_div_fixup_f32 v34, v224, v222, 1.0
	global_load_dwordx2 v[40:41], v2, s[40:41] offset:32
	global_load_dwordx2 v[42:43], v2, s[42:43] offset:32
	global_load_dwordx2 v[48:49], v2, s[40:41] offset:2080
	global_load_dwordx2 v[50:51], v2, s[42:43] offset:2080
	global_load_dwordx4 v[56:59], v176, s[60:61] offset:2048
	global_load_dwordx4 v[60:63], v176, s[60:61] offset:2112
	global_load_dwordx4 v[64:67], v182, s[60:61] offset:2048
	global_load_dwordx4 v[68:71], v182, s[60:61] offset:2112
	global_load_dwordx4 v[72:75], v181, s[100:101] offset:1024
	global_load_dwordx2 v[146:147], v8, s[0:1] offset:32
	s_mov_b32 exec_lo, 0x10001
	s_mov_b32 exec_hi, 0x10001
	global_load_dwordx4 v[44:47], v1, s[46:47] offset:-1984
	global_load_dwordx4 v[52:55], v1, s[46:47] offset:2112
	global_load_dwordx4 v[76:79], v1, s[50:51] offset:64
	global_load_dwordx4 v[80:83], v1, s[52:53] offset:64
	global_load_dwordx4 v[84:87], v1, s[58:59] offset:64
	global_load_dwordx4 v[142:145], v1, s[54:55] offset:64
	s_mov_b64 exec, -1
	s_waitcnt vmcnt(16)
	v_mov_b32_dpp v92, v92 row_newbcast:0 row_mask:0xf bank_mask:0xf
	v_mov_b32_dpp v93, v93 row_newbcast:0 row_mask:0xf bank_mask:0xf
	v_mov_b32_dpp v94, v94 row_newbcast:0 row_mask:0xf bank_mask:0xf
	v_mov_b32_dpp v95, v95 row_newbcast:0 row_mask:0xf bank_mask:0xf
	v_mov_b32_dpp v100, v100 row_newbcast:0 row_mask:0xf bank_mask:0xf
	v_mov_b32_dpp v101, v101 row_newbcast:0 row_mask:0xf bank_mask:0xf
	v_mov_b32_dpp v102, v102 row_newbcast:0 row_mask:0xf bank_mask:0xf
	v_mov_b32_dpp v103, v103 row_newbcast:0 row_mask:0xf bank_mask:0xf
	v_mov_b32_dpp v124, v124 row_newbcast:0 row_mask:0xf bank_mask:0xf
	v_mov_b32_dpp v125, v125 row_newbcast:0 row_mask:0xf bank_mask:0xf
	v_mov_b32_dpp v126, v126 row_newbcast:0 row_mask:0xf bank_mask:0xf
	v_mov_b32_dpp v127, v127 row_newbcast:0 row_mask:0xf bank_mask:0xf
	v_mov_b32_dpp v128, v128 row_newbcast:0 row_mask:0xf bank_mask:0xf
	v_mov_b32_dpp v129, v129 row_newbcast:0 row_mask:0xf bank_mask:0xf
	v_mov_b32_dpp v130, v130 row_newbcast:0 row_mask:0xf bank_mask:0xf
	v_mov_b32_dpp v131, v131 row_newbcast:0 row_mask:0xf bank_mask:0xf
	v_mov_b32_dpp v132, v132 row_newbcast:0 row_mask:0xf bank_mask:0xf
	v_mov_b32_dpp v133, v133 row_newbcast:0 row_mask:0xf bank_mask:0xf
	v_mov_b32_dpp v134, v134 row_newbcast:0 row_mask:0xf bank_mask:0xf
	v_mov_b32_dpp v135, v135 row_newbcast:0 row_mask:0xf bank_mask:0xf
	v_mov_b32_dpp v136, v136 row_newbcast:0 row_mask:0xf bank_mask:0xf
	v_mov_b32_dpp v137, v137 row_newbcast:0 row_mask:0xf bank_mask:0xf
	v_mov_b32_dpp v138, v138 row_newbcast:0 row_mask:0xf bank_mask:0xf
	v_mov_b32_dpp v139, v139 row_newbcast:0 row_mask:0xf bank_mask:0xf
	s_nop 1
	v_mfma_f32_16x16x32_bf16 v[164:167], v[104:107], v[12:15], 0
	v_mfma_f32_16x16x32_bf16 v[168:171], v[112:115], v[20:23], 0
	v_mfma_f32_16x16x32_bf16 v[172:175], v[120:123], v[28:31], 0
	v_mfma_f32_16x16x32_bf16 v[164:167], v[108:111], v[16:19], v[164:167]
	v_mfma_f32_16x16x32_bf16 v[168:171], v[116:119], v[24:27], v[168:171]
	v_and_b32_e32 v90, v5, v90
	v_and_b32_e32 v91, v5, v91
	v_lshlrev_b32_e32 v184, 16, v88
	v_and_b32_e32 v185, 0xffff0000, v88
	v_lshlrev_b32_e32 v220, 16, v90
	v_and_b32_e32 v221, 0xffff0000, v90
	v_sub_f32_e32 v220, v220, v184
	v_sub_f32_e32 v221, v221, v185
	v_fmac_f32_e32 v184, v92, v220
	v_fmac_f32_e32 v185, v93, v221
	v_lshlrev_b32_e32 v186, 16, v89
	v_and_b32_e32 v187, 0xffff0000, v89
	v_lshlrev_b32_e32 v220, 16, v91
	v_and_b32_e32 v221, 0xffff0000, v91
	v_sub_f32_e32 v220, v220, v186
	v_sub_f32_e32 v221, v221, v187
	v_fmac_f32_e32 v186, v94, v220
	v_fmac_f32_e32 v187, v95, v221
	v_and_b32_e32 v98, v5, v98
	v_and_b32_e32 v99, v5, v99
	v_lshlrev_b32_e32 v228, 16, v96
	v_and_b32_e32 v229, 0xffff0000, v96
	v_lshlrev_b32_e32 v220, 16, v98
	v_and_b32_e32 v221, 0xffff0000, v98
	v_sub_f32_e32 v220, v220, v228
	v_sub_f32_e32 v221, v221, v229
	v_fmac_f32_e32 v228, v100, v220
	v_fmac_f32_e32 v229, v101, v221
	v_lshlrev_b32_e32 v230, 16, v97
	v_and_b32_e32 v231, 0xffff0000, v97
	v_lshlrev_b32_e32 v220, 16, v99
	v_and_b32_e32 v221, 0xffff0000, v99
	v_sub_f32_e32 v220, v220, v230
	v_sub_f32_e32 v221, v221, v231
	v_fmac_f32_e32 v230, v102, v220
	v_fmac_f32_e32 v231, v103, v221
	s_nop 7
	v_add_f32_e32 v164, v124, v164
	v_add_f32_e32 v168, v128, v168
	v_add_f32_e32 v172, v136, v172
	v_add_f32_e32 v165, v125, v165
	v_add_f32_e32 v169, v129, v169
	v_add_f32_e32 v173, v137, v173
	v_add_f32_e32 v166, v126, v166
	v_add_f32_e32 v170, v130, v170
	v_add_f32_e32 v174, v138, v174
	v_add_f32_e32 v167, v127, v167
	v_add_f32_e32 v171, v131, v171
	v_add_f32_e32 v175, v139, v175
	v_mul_f32_e32 v164, 0xbfb8aa3b, v164
	v_exp_f32_e32 v164, v164
	s_nop 0
	v_add_f32_e32 v164, 1.0, v164
	v_rcp_f32_e32 v164, v164
	v_mul_f32_e32 v168, 0xbfb8aa3b, v168
	v_exp_f32_e32 v168, v168
	s_nop 0
	v_add_f32_e32 v168, 1.0, v168
	v_rcp_f32_e32 v168, v168
	v_mul_f32_e32 v172, 0xbfb8aa3b, v172
	v_exp_f32_e32 v172, v172
	s_nop 0
	v_add_f32_e32 v172, 1.0, v172
	v_rcp_f32_e32 v172, v172
	v_mul_f32_e32 v165, 0xbfb8aa3b, v165
	v_exp_f32_e32 v165, v165
	s_nop 0
	v_add_f32_e32 v165, 1.0, v165
	v_rcp_f32_e32 v165, v165
	v_mul_f32_e32 v169, 0xbfb8aa3b, v169
	v_exp_f32_e32 v169, v169
	s_nop 0
	v_add_f32_e32 v169, 1.0, v169
	v_rcp_f32_e32 v169, v169
	v_mul_f32_e32 v173, 0xbfb8aa3b, v173
	v_exp_f32_e32 v173, v173
	s_nop 0
	v_add_f32_e32 v173, 1.0, v173
	v_rcp_f32_e32 v173, v173
	v_mul_f32_e32 v166, 0xbfb8aa3b, v166
	v_exp_f32_e32 v166, v166
	s_nop 0
	v_add_f32_e32 v166, 1.0, v166
	v_rcp_f32_e32 v166, v166
	v_mul_f32_e32 v170, 0xbfb8aa3b, v170
	v_exp_f32_e32 v170, v170
	s_nop 0
	v_add_f32_e32 v170, 1.0, v170
	v_rcp_f32_e32 v170, v170
	v_mul_f32_e32 v174, 0xbfb8aa3b, v174
	v_exp_f32_e32 v174, v174
	s_nop 0
	v_add_f32_e32 v174, 1.0, v174
	v_rcp_f32_e32 v174, v174
	v_mul_f32_e32 v167, 0xbfb8aa3b, v167
	v_exp_f32_e32 v167, v167
	s_nop 0
	v_add_f32_e32 v167, 1.0, v167
	v_rcp_f32_e32 v167, v167
	v_mul_f32_e32 v171, 0xbfb8aa3b, v171
	v_exp_f32_e32 v171, v171
	s_nop 0
	v_add_f32_e32 v171, 1.0, v171
	v_rcp_f32_e32 v171, v171
	v_mul_f32_e32 v175, 0xbfb8aa3b, v175
	v_exp_f32_e32 v175, v175
	s_nop 0
	v_add_f32_e32 v175, 1.0, v175
	v_rcp_f32_e32 v175, v175
	v_mul_f32_e32 v164, 0x3f1b4598, v164
	v_mul_f32_e32 v165, 0x3f1b4598, v165
	v_mul_f32_e32 v166, 0x3f1b4598, v166
	v_mul_f32_e32 v167, 0x3f1b4598, v167
	s_cmp_eq_u32 s32, 0
	s_cbranch_scc1 .Lprep2_l0_0_0
	v_lshlrev_b32_e32 v220, 16, v140
	v_and_b32_e32 v221, 0xffff0000, v140
	v_lshlrev_b32_e32 v222, 16, v141
	v_and_b32_e32 v223, 0xffff0000, v141
	v_sub_f32_e32 v220, v220, v228
	v_fmac_f32_e32 v228, v220, v172
	v_sub_f32_e32 v221, v221, v229
	v_fmac_f32_e32 v229, v221, v173
	v_sub_f32_e32 v222, v222, v230
	v_fmac_f32_e32 v230, v222, v174
	v_sub_f32_e32 v223, v223, v231
	v_fmac_f32_e32 v231, v223, v175
	s_branch .Lprep2_l0d_0_0
.Lprep2_l0_0_0:
	v_cvt_pk_bf16_f32 v140, v228, v229
	v_cvt_pk_bf16_f32 v141, v230, v231
.Lprep2_l0d_0_0:
	global_store_dwordx2 v8, v[140:141], s[0:1] offset:0
	v_mul_f32_e32 v220, v148, v34
	v_mul_f32_e32 v224, v220, v168
	v_add_f32_e32 v168, -1.0, v168
	v_fma_f32 v168, v168, v132, 1.0
	v_mul_f32_e32 v168, v204, v168
	v_mul_f32_e32 v221, v149, v34
	v_mul_f32_e32 v225, v221, v169
	v_add_f32_e32 v169, -1.0, v169
	v_fma_f32 v169, v169, v133, 1.0
	v_mul_f32_e32 v169, v205, v169
	v_mul_f32_e32 v222, v150, v34
	v_mul_f32_e32 v226, v222, v170
	v_add_f32_e32 v170, -1.0, v170
	v_fma_f32 v170, v170, v134, 1.0
	v_mul_f32_e32 v170, v206, v170
	v_mul_f32_e32 v223, v151, v34
	v_mul_f32_e32 v227, v223, v171
	v_add_f32_e32 v171, -1.0, v171
	v_fma_f32 v171, v171, v135, 1.0
	v_mul_f32_e32 v171, v207, v171
	v_cvt_pk_bf16_f32 v88, v184, v185
	v_cvt_pk_bf16_f32 v89, v186, v187
	ds_write_b64 v9, v[88:89] offset:0
	v_cvt_pk_bf16_f32 v88, v168, v169
	v_cvt_pk_bf16_f32 v89, v170, v171
	ds_write_b64 v9, v[88:89] offset:2304
	v_cvt_pk_bf16_f32 v88, v228, v229
	v_cvt_pk_bf16_f32 v89, v230, v231
	ds_write_b64 v9, v[88:89] offset:4608
	v_cvt_pk_bf16_f32 v88, v220, v221
	v_cvt_pk_bf16_f32 v89, v222, v223
	ds_write_b64 v9, v[88:89] offset:6912
	v_cvt_pk_bf16_f32 v88, v224, v225
	v_cvt_pk_bf16_f32 v89, v226, v227
	ds_write_b64 v9, v[88:89] offset:9216
	v_cvt_pk_bf16_f32 v88, v164, v165
	v_cvt_pk_bf16_f32 v89, v166, v167
	ds_write_b64 v9, v[88:89] offset:11520
	global_load_dwordx2 v[88:89], v2, s[40:41] offset:64
	global_load_dwordx2 v[90:91], v2, s[42:43] offset:64
	global_load_dwordx2 v[96:97], v2, s[40:41] offset:2112
	global_load_dwordx2 v[98:99], v2, s[42:43] offset:2112
	global_load_dwordx4 v[104:107], v177, s[60:61] offset:0
	global_load_dwordx4 v[108:111], v177, s[60:61] offset:64
	global_load_dwordx4 v[112:115], v183, s[60:61] offset:0
	global_load_dwordx4 v[116:119], v183, s[60:61] offset:64
	global_load_dwordx4 v[120:123], v181, s[100:101] offset:2048
	global_load_dwordx2 v[140:141], v8, s[0:1] offset:64
	s_mov_b32 exec_lo, 0x10001
	s_mov_b32 exec_hi, 0x10001
	global_load_dwordx4 v[92:95], v1, s[46:47] offset:-1920
	global_load_dwordx4 v[100:103], v1, s[46:47] offset:2176
	global_load_dwordx4 v[124:127], v1, s[50:51] offset:128
	global_load_dwordx4 v[128:131], v1, s[52:53] offset:128
	global_load_dwordx4 v[132:135], v1, s[58:59] offset:128
	global_load_dwordx4 v[136:139], v1, s[54:55] offset:128
	s_mov_b64 exec, -1
	s_waitcnt vmcnt(17)
	v_mov_b32_dpp v44, v44 row_newbcast:0 row_mask:0xf bank_mask:0xf
	v_mov_b32_dpp v45, v45 row_newbcast:0 row_mask:0xf bank_mask:0xf
	v_mov_b32_dpp v46, v46 row_newbcast:0 row_mask:0xf bank_mask:0xf
	v_mov_b32_dpp v47, v47 row_newbcast:0 row_mask:0xf bank_mask:0xf
	v_mov_b32_dpp v52, v52 row_newbcast:0 row_mask:0xf bank_mask:0xf
	v_mov_b32_dpp v53, v53 row_newbcast:0 row_mask:0xf bank_mask:0xf
	v_mov_b32_dpp v54, v54 row_newbcast:0 row_mask:0xf bank_mask:0xf
	v_mov_b32_dpp v55, v55 row_newbcast:0 row_mask:0xf bank_mask:0xf
	v_mov_b32_dpp v76, v76 row_newbcast:0 row_mask:0xf bank_mask:0xf
	v_mov_b32_dpp v77, v77 row_newbcast:0 row_mask:0xf bank_mask:0xf
	v_mov_b32_dpp v78, v78 row_newbcast:0 row_mask:0xf bank_mask:0xf
	v_mov_b32_dpp v79, v79 row_newbcast:0 row_mask:0xf bank_mask:0xf
	v_mov_b32_dpp v80, v80 row_newbcast:0 row_mask:0xf bank_mask:0xf
	v_mov_b32_dpp v81, v81 row_newbcast:0 row_mask:0xf bank_mask:0xf
	v_mov_b32_dpp v82, v82 row_newbcast:0 row_mask:0xf bank_mask:0xf
	v_mov_b32_dpp v83, v83 row_newbcast:0 row_mask:0xf bank_mask:0xf
	v_mov_b32_dpp v84, v84 row_newbcast:0 row_mask:0xf bank_mask:0xf
	v_mov_b32_dpp v85, v85 row_newbcast:0 row_mask:0xf bank_mask:0xf
	v_mov_b32_dpp v86, v86 row_newbcast:0 row_mask:0xf bank_mask:0xf
	v_mov_b32_dpp v87, v87 row_newbcast:0 row_mask:0xf bank_mask:0xf
	v_mov_b32_dpp v142, v142 row_newbcast:0 row_mask:0xf bank_mask:0xf
	v_mov_b32_dpp v143, v143 row_newbcast:0 row_mask:0xf bank_mask:0xf
	v_mov_b32_dpp v144, v144 row_newbcast:0 row_mask:0xf bank_mask:0xf
	v_mov_b32_dpp v145, v145 row_newbcast:0 row_mask:0xf bank_mask:0xf
	s_nop 1
	v_mfma_f32_16x16x32_bf16 v[164:167], v[56:59], v[12:15], 0
	v_mfma_f32_16x16x32_bf16 v[168:171], v[64:67], v[20:23], 0
	v_mfma_f32_16x16x32_bf16 v[172:175], v[72:75], v[28:31], 0
	v_mfma_f32_16x16x32_bf16 v[164:167], v[60:63], v[16:19], v[164:167]
	v_mfma_f32_16x16x32_bf16 v[168:171], v[68:71], v[24:27], v[168:171]
	v_and_b32_e32 v42, v5, v42
	v_and_b32_e32 v43, v5, v43
	v_lshlrev_b32_e32 v184, 16, v40
	v_and_b32_e32 v185, 0xffff0000, v40
	v_lshlrev_b32_e32 v220, 16, v42
	v_and_b32_e32 v221, 0xffff0000, v42
	v_sub_f32_e32 v220, v220, v184
	v_sub_f32_e32 v221, v221, v185
	v_fmac_f32_e32 v184, v44, v220
	v_fmac_f32_e32 v185, v45, v221
	v_lshlrev_b32_e32 v186, 16, v41
	v_and_b32_e32 v187, 0xffff0000, v41
	v_lshlrev_b32_e32 v220, 16, v43
	v_and_b32_e32 v221, 0xffff0000, v43
	v_sub_f32_e32 v220, v220, v186
	v_sub_f32_e32 v221, v221, v187
	v_fmac_f32_e32 v186, v46, v220
	v_fmac_f32_e32 v187, v47, v221
	v_and_b32_e32 v50, v5, v50
	v_and_b32_e32 v51, v5, v51
	v_lshlrev_b32_e32 v228, 16, v48
	v_and_b32_e32 v229, 0xffff0000, v48
	v_lshlrev_b32_e32 v220, 16, v50
	v_and_b32_e32 v221, 0xffff0000, v50
	v_sub_f32_e32 v220, v220, v228
	v_sub_f32_e32 v221, v221, v229
	v_fmac_f32_e32 v228, v52, v220
	v_fmac_f32_e32 v229, v53, v221
	v_lshlrev_b32_e32 v230, 16, v49
	v_and_b32_e32 v231, 0xffff0000, v49
	v_lshlrev_b32_e32 v220, 16, v51
	v_and_b32_e32 v221, 0xffff0000, v51
	v_sub_f32_e32 v220, v220, v230
	v_sub_f32_e32 v221, v221, v231
	v_fmac_f32_e32 v230, v54, v220
	v_fmac_f32_e32 v231, v55, v221
	s_nop 7
	v_add_f32_e32 v164, v76, v164
	v_add_f32_e32 v168, v80, v168
	v_add_f32_e32 v172, v142, v172
	v_add_f32_e32 v165, v77, v165
	v_add_f32_e32 v169, v81, v169
	v_add_f32_e32 v173, v143, v173
	v_add_f32_e32 v166, v78, v166
	v_add_f32_e32 v170, v82, v170
	v_add_f32_e32 v174, v144, v174
	v_add_f32_e32 v167, v79, v167
	v_add_f32_e32 v171, v83, v171
	v_add_f32_e32 v175, v145, v175
	v_mul_f32_e32 v164, 0xbfb8aa3b, v164
	v_exp_f32_e32 v164, v164
	s_nop 0
	v_add_f32_e32 v164, 1.0, v164
	v_rcp_f32_e32 v164, v164
	v_mul_f32_e32 v168, 0xbfb8aa3b, v168
	v_exp_f32_e32 v168, v168
	s_nop 0
	v_add_f32_e32 v168, 1.0, v168
	v_rcp_f32_e32 v168, v168
	v_mul_f32_e32 v172, 0xbfb8aa3b, v172
	v_exp_f32_e32 v172, v172
	s_nop 0
	v_add_f32_e32 v172, 1.0, v172
	v_rcp_f32_e32 v172, v172
	v_mul_f32_e32 v165, 0xbfb8aa3b, v165
	v_exp_f32_e32 v165, v165
	s_nop 0
	v_add_f32_e32 v165, 1.0, v165
	v_rcp_f32_e32 v165, v165
	v_mul_f32_e32 v169, 0xbfb8aa3b, v169
	v_exp_f32_e32 v169, v169
	s_nop 0
	v_add_f32_e32 v169, 1.0, v169
	v_rcp_f32_e32 v169, v169
	v_mul_f32_e32 v173, 0xbfb8aa3b, v173
	v_exp_f32_e32 v173, v173
	s_nop 0
	v_add_f32_e32 v173, 1.0, v173
	v_rcp_f32_e32 v173, v173
	v_mul_f32_e32 v166, 0xbfb8aa3b, v166
	v_exp_f32_e32 v166, v166
	s_nop 0
	v_add_f32_e32 v166, 1.0, v166
	v_rcp_f32_e32 v166, v166
	v_mul_f32_e32 v170, 0xbfb8aa3b, v170
	v_exp_f32_e32 v170, v170
	s_nop 0
	v_add_f32_e32 v170, 1.0, v170
	v_rcp_f32_e32 v170, v170
	v_mul_f32_e32 v174, 0xbfb8aa3b, v174
	v_exp_f32_e32 v174, v174
	s_nop 0
	v_add_f32_e32 v174, 1.0, v174
	v_rcp_f32_e32 v174, v174
	v_mul_f32_e32 v167, 0xbfb8aa3b, v167
	v_exp_f32_e32 v167, v167
	s_nop 0
	v_add_f32_e32 v167, 1.0, v167
	v_rcp_f32_e32 v167, v167
	v_mul_f32_e32 v171, 0xbfb8aa3b, v171
	v_exp_f32_e32 v171, v171
	s_nop 0
	v_add_f32_e32 v171, 1.0, v171
	v_rcp_f32_e32 v171, v171
	v_mul_f32_e32 v175, 0xbfb8aa3b, v175
	v_exp_f32_e32 v175, v175
	s_nop 0
	v_add_f32_e32 v175, 1.0, v175
	v_rcp_f32_e32 v175, v175
	v_mul_f32_e32 v164, 0x3f1b4598, v164
	v_mul_f32_e32 v165, 0x3f1b4598, v165
	v_mul_f32_e32 v166, 0x3f1b4598, v166
	v_mul_f32_e32 v167, 0x3f1b4598, v167
	s_cmp_eq_u32 s32, 0
	s_cbranch_scc1 .Lprep2_l0_0_1
	v_lshlrev_b32_e32 v220, 16, v146
	v_and_b32_e32 v221, 0xffff0000, v146
	v_lshlrev_b32_e32 v222, 16, v147
	v_and_b32_e32 v223, 0xffff0000, v147
	v_sub_f32_e32 v220, v220, v228
	v_fmac_f32_e32 v228, v220, v172
	v_sub_f32_e32 v221, v221, v229
	v_fmac_f32_e32 v229, v221, v173
	v_sub_f32_e32 v222, v222, v230
	v_fmac_f32_e32 v230, v222, v174
	v_sub_f32_e32 v223, v223, v231
	v_fmac_f32_e32 v231, v223, v175
	s_branch .Lprep2_l0d_0_1
.Lprep2_l0_0_1:
	v_cvt_pk_bf16_f32 v146, v228, v229
	v_cvt_pk_bf16_f32 v147, v230, v231
.Lprep2_l0d_0_1:
	global_store_dwordx2 v8, v[146:147], s[0:1] offset:32
	v_mul_f32_e32 v220, v152, v34
	v_mul_f32_e32 v224, v220, v168
	v_add_f32_e32 v168, -1.0, v168
	v_fma_f32 v168, v168, v84, 1.0
	v_mul_f32_e32 v168, v208, v168
	v_mul_f32_e32 v221, v153, v34
	v_mul_f32_e32 v225, v221, v169
	v_add_f32_e32 v169, -1.0, v169
	v_fma_f32 v169, v169, v85, 1.0
	v_mul_f32_e32 v169, v209, v169
	v_mul_f32_e32 v222, v154, v34
	v_mul_f32_e32 v226, v222, v170
	v_add_f32_e32 v170, -1.0, v170
	v_fma_f32 v170, v170, v86, 1.0
	v_mul_f32_e32 v170, v210, v170
	v_mul_f32_e32 v223, v155, v34
	v_mul_f32_e32 v227, v223, v171
	v_add_f32_e32 v171, -1.0, v171
	v_fma_f32 v171, v171, v87, 1.0
	v_mul_f32_e32 v171, v211, v171
	v_cvt_pk_bf16_f32 v40, v184, v185
	v_cvt_pk_bf16_f32 v41, v186, v187
	ds_write_b64 v9, v[40:41] offset:32
	v_cvt_pk_bf16_f32 v40, v168, v169
	v_cvt_pk_bf16_f32 v41, v170, v171
	ds_write_b64 v9, v[40:41] offset:2336
	v_cvt_pk_bf16_f32 v40, v228, v229
	v_cvt_pk_bf16_f32 v41, v230, v231
	ds_write_b64 v9, v[40:41] offset:4640
	v_cvt_pk_bf16_f32 v40, v220, v221
	v_cvt_pk_bf16_f32 v41, v222, v223
	ds_write_b64 v9, v[40:41] offset:6944
	v_cvt_pk_bf16_f32 v40, v224, v225
	v_cvt_pk_bf16_f32 v41, v226, v227
	ds_write_b64 v9, v[40:41] offset:9248
	v_cvt_pk_bf16_f32 v40, v164, v165
	v_cvt_pk_bf16_f32 v41, v166, v167
	ds_write_b64 v9, v[40:41] offset:11552
	global_load_dwordx2 v[40:41], v2, s[40:41] offset:96
	global_load_dwordx2 v[42:43], v2, s[42:43] offset:96
	global_load_dwordx2 v[48:49], v2, s[40:41] offset:2144
	global_load_dwordx2 v[50:51], v2, s[42:43] offset:2144
	global_load_dwordx4 v[56:59], v177, s[60:61] offset:2048
	global_load_dwordx4 v[60:63], v177, s[60:61] offset:2112
	global_load_dwordx4 v[64:67], v183, s[60:61] offset:2048
	global_load_dwordx4 v[68:71], v183, s[60:61] offset:2112
	global_load_dwordx4 v[72:75], v181, s[100:101] offset:3072
	global_load_dwordx2 v[146:147], v8, s[0:1] offset:96
	s_mov_b32 exec_lo, 0x10001
	s_mov_b32 exec_hi, 0x10001
	global_load_dwordx4 v[44:47], v1, s[46:47] offset:-1856
	global_load_dwordx4 v[52:55], v1, s[46:47] offset:2240
	global_load_dwordx4 v[76:79], v1, s[50:51] offset:192
	global_load_dwordx4 v[80:83], v1, s[52:53] offset:192
	global_load_dwordx4 v[84:87], v1, s[58:59] offset:192
	global_load_dwordx4 v[142:145], v1, s[54:55] offset:192
	s_mov_b64 exec, -1
	s_waitcnt vmcnt(17)
	v_mov_b32_dpp v92, v92 row_newbcast:0 row_mask:0xf bank_mask:0xf
	v_mov_b32_dpp v93, v93 row_newbcast:0 row_mask:0xf bank_mask:0xf
	v_mov_b32_dpp v94, v94 row_newbcast:0 row_mask:0xf bank_mask:0xf
	v_mov_b32_dpp v95, v95 row_newbcast:0 row_mask:0xf bank_mask:0xf
	v_mov_b32_dpp v100, v100 row_newbcast:0 row_mask:0xf bank_mask:0xf
	v_mov_b32_dpp v101, v101 row_newbcast:0 row_mask:0xf bank_mask:0xf
	v_mov_b32_dpp v102, v102 row_newbcast:0 row_mask:0xf bank_mask:0xf
	v_mov_b32_dpp v103, v103 row_newbcast:0 row_mask:0xf bank_mask:0xf
	v_mov_b32_dpp v124, v124 row_newbcast:0 row_mask:0xf bank_mask:0xf
	v_mov_b32_dpp v125, v125 row_newbcast:0 row_mask:0xf bank_mask:0xf
	v_mov_b32_dpp v126, v126 row_newbcast:0 row_mask:0xf bank_mask:0xf
	v_mov_b32_dpp v127, v127 row_newbcast:0 row_mask:0xf bank_mask:0xf
	v_mov_b32_dpp v128, v128 row_newbcast:0 row_mask:0xf bank_mask:0xf
	v_mov_b32_dpp v129, v129 row_newbcast:0 row_mask:0xf bank_mask:0xf
	v_mov_b32_dpp v130, v130 row_newbcast:0 row_mask:0xf bank_mask:0xf
	v_mov_b32_dpp v131, v131 row_newbcast:0 row_mask:0xf bank_mask:0xf
	v_mov_b32_dpp v132, v132 row_newbcast:0 row_mask:0xf bank_mask:0xf
	v_mov_b32_dpp v133, v133 row_newbcast:0 row_mask:0xf bank_mask:0xf
	v_mov_b32_dpp v134, v134 row_newbcast:0 row_mask:0xf bank_mask:0xf
	v_mov_b32_dpp v135, v135 row_newbcast:0 row_mask:0xf bank_mask:0xf
	v_mov_b32_dpp v136, v136 row_newbcast:0 row_mask:0xf bank_mask:0xf
	v_mov_b32_dpp v137, v137 row_newbcast:0 row_mask:0xf bank_mask:0xf
	v_mov_b32_dpp v138, v138 row_newbcast:0 row_mask:0xf bank_mask:0xf
	v_mov_b32_dpp v139, v139 row_newbcast:0 row_mask:0xf bank_mask:0xf
	s_nop 1
	v_mfma_f32_16x16x32_bf16 v[164:167], v[104:107], v[12:15], 0
	v_mfma_f32_16x16x32_bf16 v[168:171], v[112:115], v[20:23], 0
	v_mfma_f32_16x16x32_bf16 v[172:175], v[120:123], v[28:31], 0
	v_mfma_f32_16x16x32_bf16 v[164:167], v[108:111], v[16:19], v[164:167]
	v_mfma_f32_16x16x32_bf16 v[168:171], v[116:119], v[24:27], v[168:171]
	v_and_b32_e32 v90, v5, v90
	v_and_b32_e32 v91, v5, v91
	v_lshlrev_b32_e32 v184, 16, v88
	v_and_b32_e32 v185, 0xffff0000, v88
	v_lshlrev_b32_e32 v220, 16, v90
	v_and_b32_e32 v221, 0xffff0000, v90
	v_sub_f32_e32 v220, v220, v184
	v_sub_f32_e32 v221, v221, v185
	v_fmac_f32_e32 v184, v92, v220
	v_fmac_f32_e32 v185, v93, v221
	v_lshlrev_b32_e32 v186, 16, v89
	v_and_b32_e32 v187, 0xffff0000, v89
	v_lshlrev_b32_e32 v220, 16, v91
	v_and_b32_e32 v221, 0xffff0000, v91
	v_sub_f32_e32 v220, v220, v186
	v_sub_f32_e32 v221, v221, v187
	v_fmac_f32_e32 v186, v94, v220
	v_fmac_f32_e32 v187, v95, v221
	v_and_b32_e32 v98, v5, v98
	v_and_b32_e32 v99, v5, v99
	v_lshlrev_b32_e32 v228, 16, v96
	v_and_b32_e32 v229, 0xffff0000, v96
	v_lshlrev_b32_e32 v220, 16, v98
	v_and_b32_e32 v221, 0xffff0000, v98
	v_sub_f32_e32 v220, v220, v228
	v_sub_f32_e32 v221, v221, v229
	v_fmac_f32_e32 v228, v100, v220
	v_fmac_f32_e32 v229, v101, v221
	v_lshlrev_b32_e32 v230, 16, v97
	v_and_b32_e32 v231, 0xffff0000, v97
	v_lshlrev_b32_e32 v220, 16, v99
	v_and_b32_e32 v221, 0xffff0000, v99
	v_sub_f32_e32 v220, v220, v230
	v_sub_f32_e32 v221, v221, v231
	v_fmac_f32_e32 v230, v102, v220
	v_fmac_f32_e32 v231, v103, v221
	s_nop 7
	v_add_f32_e32 v164, v124, v164
	v_add_f32_e32 v168, v128, v168
	v_add_f32_e32 v172, v136, v172
	v_add_f32_e32 v165, v125, v165
	v_add_f32_e32 v169, v129, v169
	v_add_f32_e32 v173, v137, v173
	v_add_f32_e32 v166, v126, v166
	v_add_f32_e32 v170, v130, v170
	v_add_f32_e32 v174, v138, v174
	v_add_f32_e32 v167, v127, v167
	v_add_f32_e32 v171, v131, v171
	v_add_f32_e32 v175, v139, v175
	v_mul_f32_e32 v164, 0xbfb8aa3b, v164
	v_exp_f32_e32 v164, v164
	s_nop 0
	v_add_f32_e32 v164, 1.0, v164
	v_rcp_f32_e32 v164, v164
	v_mul_f32_e32 v168, 0xbfb8aa3b, v168
	v_exp_f32_e32 v168, v168
	s_nop 0
	v_add_f32_e32 v168, 1.0, v168
	v_rcp_f32_e32 v168, v168
	v_mul_f32_e32 v172, 0xbfb8aa3b, v172
	v_exp_f32_e32 v172, v172
	s_nop 0
	v_add_f32_e32 v172, 1.0, v172
	v_rcp_f32_e32 v172, v172
	v_mul_f32_e32 v165, 0xbfb8aa3b, v165
	v_exp_f32_e32 v165, v165
	s_nop 0
	v_add_f32_e32 v165, 1.0, v165
	v_rcp_f32_e32 v165, v165
	v_mul_f32_e32 v169, 0xbfb8aa3b, v169
	v_exp_f32_e32 v169, v169
	s_nop 0
	v_add_f32_e32 v169, 1.0, v169
	v_rcp_f32_e32 v169, v169
	v_mul_f32_e32 v173, 0xbfb8aa3b, v173
	v_exp_f32_e32 v173, v173
	s_nop 0
	v_add_f32_e32 v173, 1.0, v173
	v_rcp_f32_e32 v173, v173
	v_mul_f32_e32 v166, 0xbfb8aa3b, v166
	v_exp_f32_e32 v166, v166
	s_nop 0
	v_add_f32_e32 v166, 1.0, v166
	v_rcp_f32_e32 v166, v166
	v_mul_f32_e32 v170, 0xbfb8aa3b, v170
	v_exp_f32_e32 v170, v170
	s_nop 0
	v_add_f32_e32 v170, 1.0, v170
	v_rcp_f32_e32 v170, v170
	v_mul_f32_e32 v174, 0xbfb8aa3b, v174
	v_exp_f32_e32 v174, v174
	s_nop 0
	v_add_f32_e32 v174, 1.0, v174
	v_rcp_f32_e32 v174, v174
	v_mul_f32_e32 v167, 0xbfb8aa3b, v167
	v_exp_f32_e32 v167, v167
	s_nop 0
	v_add_f32_e32 v167, 1.0, v167
	v_rcp_f32_e32 v167, v167
	v_mul_f32_e32 v171, 0xbfb8aa3b, v171
	v_exp_f32_e32 v171, v171
	s_nop 0
	v_add_f32_e32 v171, 1.0, v171
	v_rcp_f32_e32 v171, v171
	v_mul_f32_e32 v175, 0xbfb8aa3b, v175
	v_exp_f32_e32 v175, v175
	s_nop 0
	v_add_f32_e32 v175, 1.0, v175
	v_rcp_f32_e32 v175, v175
	v_mul_f32_e32 v164, 0x3f1b4598, v164
	v_mul_f32_e32 v165, 0x3f1b4598, v165
	v_mul_f32_e32 v166, 0x3f1b4598, v166
	v_mul_f32_e32 v167, 0x3f1b4598, v167
	s_cmp_eq_u32 s32, 0
	s_cbranch_scc1 .Lprep2_l0_0_2
	v_lshlrev_b32_e32 v220, 16, v140
	v_and_b32_e32 v221, 0xffff0000, v140
	v_lshlrev_b32_e32 v222, 16, v141
	v_and_b32_e32 v223, 0xffff0000, v141
	v_sub_f32_e32 v220, v220, v228
	v_fmac_f32_e32 v228, v220, v172
	v_sub_f32_e32 v221, v221, v229
	v_fmac_f32_e32 v229, v221, v173
	v_sub_f32_e32 v222, v222, v230
	v_fmac_f32_e32 v230, v222, v174
	v_sub_f32_e32 v223, v223, v231
	v_fmac_f32_e32 v231, v223, v175
	s_branch .Lprep2_l0d_0_2

.Lprep2_l0d_0_2:
	global_store_dwordx2 v8, v[140:141], s[0:1] offset:64
	v_mul_f32_e32 v220, v156, v34
	v_mul_f32_e32 v224, v220, v168
	v_add_f32_e32 v168, -1.0, v168
	v_fma_f32 v168, v168, v132, 1.0
	v_mul_f32_e32 v168, v212, v168
	v_mul_f32_e32 v221, v157, v34
	v_mul_f32_e32 v225, v221, v169
	v_add_f32_e32 v169, -1.0, v169
	v_fma_f32 v169, v169, v133, 1.0
	v_mul_f32_e32 v169, v213, v169
	v_mul_f32_e32 v222, v158, v34
	v_mul_f32_e32 v226, v222, v170
	v_add_f32_e32 v170, -1.0, v170
	v_fma_f32 v170, v170, v134, 1.0
	v_mul_f32_e32 v170, v214, v170
	v_mul_f32_e32 v223, v159, v34
	v_mul_f32_e32 v227, v223, v171
	v_add_f32_e32 v171, -1.0, v171
	v_fma_f32 v171, v171, v135, 1.0
	v_mul_f32_e32 v171, v215, v171
	v_cvt_pk_bf16_f32 v88, v184, v185
	v_cvt_pk_bf16_f32 v89, v186, v187
	ds_write_b64 v9, v[88:89] offset:64
	v_cvt_pk_bf16_f32 v88, v168, v169
	v_cvt_pk_bf16_f32 v89, v170, v171
	ds_write_b64 v9, v[88:89] offset:2368
	v_cvt_pk_bf16_f32 v88, v228, v229
	v_cvt_pk_bf16_f32 v89, v230, v231
	ds_write_b64 v9, v[88:89] offset:4672
	v_cvt_pk_bf16_f32 v88, v220, v221
	v_cvt_pk_bf16_f32 v89, v222, v223
	ds_write_b64 v9, v[88:89] offset:6976
	v_cvt_pk_bf16_f32 v88, v224, v225
	v_cvt_pk_bf16_f32 v89, v226, v227
	ds_write_b64 v9, v[88:89] offset:9280
	v_cvt_pk_bf16_f32 v88, v164, v165
	v_cvt_pk_bf16_f32 v89, v166, v167
	ds_write_b64 v9, v[88:89] offset:11584
	s_waitcnt vmcnt(1)
	v_mov_b32_dpp v44, v44 row_newbcast:0 row_mask:0xf bank_mask:0xf
	v_mov_b32_dpp v45, v45 row_newbcast:0 row_mask:0xf bank_mask:0xf
	v_mov_b32_dpp v46, v46 row_newbcast:0 row_mask:0xf bank_mask:0xf
	v_mov_b32_dpp v47, v47 row_newbcast:0 row_mask:0xf bank_mask:0xf
	v_mov_b32_dpp v52, v52 row_newbcast:0 row_mask:0xf bank_mask:0xf
	v_mov_b32_dpp v53, v53 row_newbcast:0 row_mask:0xf bank_mask:0xf
	v_mov_b32_dpp v54, v54 row_newbcast:0 row_mask:0xf bank_mask:0xf
	v_mov_b32_dpp v55, v55 row_newbcast:0 row_mask:0xf bank_mask:0xf
	v_mov_b32_dpp v76, v76 row_newbcast:0 row_mask:0xf bank_mask:0xf
	v_mov_b32_dpp v77, v77 row_newbcast:0 row_mask:0xf bank_mask:0xf
	v_mov_b32_dpp v78, v78 row_newbcast:0 row_mask:0xf bank_mask:0xf
	v_mov_b32_dpp v79, v79 row_newbcast:0 row_mask:0xf bank_mask:0xf
	v_mov_b32_dpp v80, v80 row_newbcast:0 row_mask:0xf bank_mask:0xf
	v_mov_b32_dpp v81, v81 row_newbcast:0 row_mask:0xf bank_mask:0xf
	v_mov_b32_dpp v82, v82 row_newbcast:0 row_mask:0xf bank_mask:0xf
	v_mov_b32_dpp v83, v83 row_newbcast:0 row_mask:0xf bank_mask:0xf
	v_mov_b32_dpp v84, v84 row_newbcast:0 row_mask:0xf bank_mask:0xf
	v_mov_b32_dpp v85, v85 row_newbcast:0 row_mask:0xf bank_mask:0xf
	v_mov_b32_dpp v86, v86 row_newbcast:0 row_mask:0xf bank_mask:0xf
	v_mov_b32_dpp v87, v87 row_newbcast:0 row_mask:0xf bank_mask:0xf
	v_mov_b32_dpp v142, v142 row_newbcast:0 row_mask:0xf bank_mask:0xf
	v_mov_b32_dpp v143, v143 row_newbcast:0 row_mask:0xf bank_mask:0xf
	v_mov_b32_dpp v144, v144 row_newbcast:0 row_mask:0xf bank_mask:0xf
	v_mov_b32_dpp v145, v145 row_newbcast:0 row_mask:0xf bank_mask:0xf
	s_nop 1
	v_mfma_f32_16x16x32_bf16 v[164:167], v[56:59], v[12:15], 0
	v_mfma_f32_16x16x32_bf16 v[168:171], v[64:67], v[20:23], 0
	v_mfma_f32_16x16x32_bf16 v[172:175], v[72:75], v[28:31], 0
	v_mfma_f32_16x16x32_bf16 v[164:167], v[60:63], v[16:19], v[164:167]
	v_mfma_f32_16x16x32_bf16 v[168:171], v[68:71], v[24:27], v[168:171]
	v_and_b32_e32 v42, v5, v42
	v_and_b32_e32 v43, v5, v43
	v_lshlrev_b32_e32 v184, 16, v40
	v_and_b32_e32 v185, 0xffff0000, v40
	v_lshlrev_b32_e32 v220, 16, v42
	v_and_b32_e32 v221, 0xffff0000, v42
	v_sub_f32_e32 v220, v220, v184
	v_sub_f32_e32 v221, v221, v185
	v_fmac_f32_e32 v184, v44, v220
	v_fmac_f32_e32 v185, v45, v221
	v_lshlrev_b32_e32 v186, 16, v41
	v_and_b32_e32 v187, 0xffff0000, v41
	v_lshlrev_b32_e32 v220, 16, v43
	v_and_b32_e32 v221, 0xffff0000, v43
	v_sub_f32_e32 v220, v220, v186
	v_sub_f32_e32 v221, v221, v187
	v_fmac_f32_e32 v186, v46, v220
	v_fmac_f32_e32 v187, v47, v221
	v_and_b32_e32 v50, v5, v50
	v_and_b32_e32 v51, v5, v51
	v_lshlrev_b32_e32 v228, 16, v48
	v_and_b32_e32 v229, 0xffff0000, v48
	v_lshlrev_b32_e32 v220, 16, v50
	v_and_b32_e32 v221, 0xffff0000, v50
	v_sub_f32_e32 v220, v220, v228
	v_sub_f32_e32 v221, v221, v229
	v_fmac_f32_e32 v228, v52, v220
	v_fmac_f32_e32 v229, v53, v221
	v_lshlrev_b32_e32 v230, 16, v49
	v_and_b32_e32 v231, 0xffff0000, v49
	v_lshlrev_b32_e32 v220, 16, v51
	v_and_b32_e32 v221, 0xffff0000, v51
	v_sub_f32_e32 v220, v220, v230
	v_sub_f32_e32 v221, v221, v231
	v_fmac_f32_e32 v230, v54, v220
	v_fmac_f32_e32 v231, v55, v221
	s_nop 7
	v_add_f32_e32 v164, v76, v164
	v_add_f32_e32 v168, v80, v168
	v_add_f32_e32 v172, v142, v172
	v_add_f32_e32 v165, v77, v165
	v_add_f32_e32 v169, v81, v169
	v_add_f32_e32 v173, v143, v173
	v_add_f32_e32 v166, v78, v166
	v_add_f32_e32 v170, v82, v170
	v_add_f32_e32 v174, v144, v174
	v_add_f32_e32 v167, v79, v167
	v_add_f32_e32 v171, v83, v171
	v_add_f32_e32 v175, v145, v175
	v_mul_f32_e32 v164, 0xbfb8aa3b, v164
	v_exp_f32_e32 v164, v164
	s_nop 0
	v_add_f32_e32 v164, 1.0, v164
	v_rcp_f32_e32 v164, v164
	v_mul_f32_e32 v168, 0xbfb8aa3b, v168
	v_exp_f32_e32 v168, v168
	s_nop 0
	v_add_f32_e32 v168, 1.0, v168
	v_rcp_f32_e32 v168, v168
	v_mul_f32_e32 v172, 0xbfb8aa3b, v172
	v_exp_f32_e32 v172, v172
	s_nop 0
	v_add_f32_e32 v172, 1.0, v172
	v_rcp_f32_e32 v172, v172
	v_mul_f32_e32 v165, 0xbfb8aa3b, v165
	v_exp_f32_e32 v165, v165
	s_nop 0
	v_add_f32_e32 v165, 1.0, v165
	v_rcp_f32_e32 v165, v165
	v_mul_f32_e32 v169, 0xbfb8aa3b, v169
	v_exp_f32_e32 v169, v169
	s_nop 0
	v_add_f32_e32 v169, 1.0, v169
	v_rcp_f32_e32 v169, v169
	v_mul_f32_e32 v173, 0xbfb8aa3b, v173
	v_exp_f32_e32 v173, v173
	s_nop 0
	v_add_f32_e32 v173, 1.0, v173
	v_rcp_f32_e32 v173, v173
	v_mul_f32_e32 v166, 0xbfb8aa3b, v166
	v_exp_f32_e32 v166, v166
	s_nop 0
	v_add_f32_e32 v166, 1.0, v166
	v_rcp_f32_e32 v166, v166
	v_mul_f32_e32 v170, 0xbfb8aa3b, v170
	v_exp_f32_e32 v170, v170
	s_nop 0
	v_add_f32_e32 v170, 1.0, v170
	v_rcp_f32_e32 v170, v170
	v_mul_f32_e32 v174, 0xbfb8aa3b, v174
	v_exp_f32_e32 v174, v174
	s_nop 0
	v_add_f32_e32 v174, 1.0, v174
	v_rcp_f32_e32 v174, v174
	v_mul_f32_e32 v167, 0xbfb8aa3b, v167
	v_exp_f32_e32 v167, v167
	s_nop 0
	v_add_f32_e32 v167, 1.0, v167
	v_rcp_f32_e32 v167, v167
	v_mul_f32_e32 v171, 0xbfb8aa3b, v171
	v_exp_f32_e32 v171, v171
	s_nop 0
	v_add_f32_e32 v171, 1.0, v171
	v_rcp_f32_e32 v171, v171
	v_mul_f32_e32 v175, 0xbfb8aa3b, v175
	v_exp_f32_e32 v175, v175
	s_nop 0
	v_add_f32_e32 v175, 1.0, v175
	v_rcp_f32_e32 v175, v175
	v_mul_f32_e32 v164, 0x3f1b4598, v164
	v_mul_f32_e32 v165, 0x3f1b4598, v165
	v_mul_f32_e32 v166, 0x3f1b4598, v166
	v_mul_f32_e32 v167, 0x3f1b4598, v167
	s_cmp_eq_u32 s32, 0
	s_cbranch_scc1 .Lprep2_l0_0_3
	v_lshlrev_b32_e32 v220, 16, v146
	v_and_b32_e32 v221, 0xffff0000, v146
	v_lshlrev_b32_e32 v222, 16, v147
	v_and_b32_e32 v223, 0xffff0000, v147
	v_sub_f32_e32 v220, v220, v228
	v_fmac_f32_e32 v228, v220, v172
	v_sub_f32_e32 v221, v221, v229
	v_fmac_f32_e32 v229, v221, v173
	v_sub_f32_e32 v222, v222, v230
	v_fmac_f32_e32 v230, v222, v174
	v_sub_f32_e32 v223, v223, v231
	v_fmac_f32_e32 v231, v223, v175
	s_branch .Lprep2_l0d_0_3

.Lprep2_l0d_0_3:
	global_store_dwordx2 v8, v[146:147], s[0:1] offset:96
	v_mul_f32_e32 v220, v160, v34
	v_mul_f32_e32 v224, v220, v168
	v_add_f32_e32 v168, -1.0, v168
	v_fma_f32 v168, v168, v84, 1.0
	v_mul_f32_e32 v168, v216, v168
	v_mul_f32_e32 v221, v161, v34
	v_mul_f32_e32 v225, v221, v169
	v_add_f32_e32 v169, -1.0, v169
	v_fma_f32 v169, v169, v85, 1.0
	v_mul_f32_e32 v169, v217, v169
	v_mul_f32_e32 v222, v162, v34
	v_mul_f32_e32 v226, v222, v170
	v_add_f32_e32 v170, -1.0, v170
	v_fma_f32 v170, v170, v86, 1.0
	v_mul_f32_e32 v170, v218, v170
	v_mul_f32_e32 v223, v163, v34
	v_mul_f32_e32 v227, v223, v171
	v_add_f32_e32 v171, -1.0, v171
	v_fma_f32 v171, v171, v87, 1.0
	v_mul_f32_e32 v171, v219, v171
	v_cvt_pk_bf16_f32 v40, v184, v185
	v_cvt_pk_bf16_f32 v41, v186, v187
	ds_write_b64 v9, v[40:41] offset:96
	v_cvt_pk_bf16_f32 v40, v168, v169
	v_cvt_pk_bf16_f32 v41, v170, v171
	ds_write_b64 v9, v[40:41] offset:2400
	v_cvt_pk_bf16_f32 v40, v228, v229
	v_cvt_pk_bf16_f32 v41, v230, v231
	ds_write_b64 v9, v[40:41] offset:4704
	v_cvt_pk_bf16_f32 v40, v220, v221
	v_cvt_pk_bf16_f32 v41, v222, v223
	ds_write_b64 v9, v[40:41] offset:7008
	v_cvt_pk_bf16_f32 v40, v224, v225
	v_cvt_pk_bf16_f32 v41, v226, v227
	ds_write_b64 v9, v[40:41] offset:9312
	v_cvt_pk_bf16_f32 v40, v164, v165
	v_cvt_pk_bf16_f32 v41, v166, v167
	ds_write_b64 v9, v[40:41] offset:11616
	v_add_u32_e32 v176, 0x2000, v6
	v_add_u32_e32 v177, 0x3000, v6
	v_add_u32_e32 v181, 0x1000, v7
	v_add_u32_e32 v182, 0x42000, v6
	v_add_u32_e32 v183, 0x43000, v6
	s_waitcnt lgkmcnt(0)
	ds_read_b128 v[148:151], v10 offset:0
	ds_read_b128 v[152:155], v10 offset:1152
	ds_read_b128 v[156:159], v10 offset:2304
	ds_read_b128 v[160:163], v10 offset:3456
	ds_read_b128 v[204:207], v10 offset:4608
	ds_read_b128 v[208:211], v10 offset:5760
	ds_read_b128 v[212:215], v10 offset:6912
	ds_read_b128 v[216:219], v10 offset:8064
	ds_read_b128 v[164:167], v10 offset:9216
	ds_read_b128 v[168:171], v10 offset:10368
	ds_read_b128 v[172:175], v10 offset:11520
	ds_read_b128 v[220:223], v10 offset:12672
	global_load_dwordx2 v[40:41], v2, s[40:41] offset:1152
	global_load_dwordx2 v[42:43], v2, s[42:43] offset:1152
	global_load_dwordx2 v[52:53], v2, s[40:41] offset:1184
	global_load_dwordx2 v[54:55], v2, s[42:43] offset:1184
	global_load_dwordx2 v[64:65], v2, s[40:41] offset:1216
	global_load_dwordx2 v[66:67], v2, s[42:43] offset:1216
	global_load_dwordx2 v[76:77], v2, s[40:41] offset:1248
	global_load_dwordx2 v[78:79], v2, s[42:43] offset:1248
	s_mov_b32 exec_lo, 0x10001
	s_mov_b32 exec_hi, 0x10001
	global_load_dwordx4 v[44:47], v1, s[46:47] offset:256
	global_load_dwordx4 v[48:51], v1, s[56:57] offset:256
	global_load_dwordx4 v[56:59], v1, s[46:47] offset:320
	global_load_dwordx4 v[60:63], v1, s[56:57] offset:320
	global_load_dwordx4 v[68:71], v1, s[46:47] offset:384
	global_load_dwordx4 v[72:75], v1, s[56:57] offset:384
	global_load_dwordx4 v[80:83], v1, s[46:47] offset:448
	global_load_dwordx4 v[84:87], v1, s[56:57] offset:448
	s_mov_b64 exec, -1
	global_load_dwordx2 v[88:89], v2, s[40:41] offset:128
	global_load_dwordx2 v[90:91], v2, s[42:43] offset:128
	global_load_dwordx2 v[96:97], v2, s[40:41] offset:2176
	global_load_dwordx2 v[98:99], v2, s[42:43] offset:2176
	global_load_dwordx4 v[104:107], v176, s[60:61] offset:0
	global_load_dwordx4 v[108:111], v176, s[60:61] offset:64
	global_load_dwordx4 v[112:115], v182, s[60:61] offset:0
	global_load_dwordx4 v[116:119], v182, s[60:61] offset:64
	global_load_dwordx4 v[120:123], v181, s[100:101] offset:0
	global_load_dwordx2 v[140:141], v8, s[0:1] offset:128
	s_mov_b32 exec_lo, 0x10001
	s_mov_b32 exec_hi, 0x10001
	global_load_dwordx4 v[92:95], v1, s[46:47] offset:-1792
	global_load_dwordx4 v[100:103], v1, s[46:47] offset:2304
	global_load_dwordx4 v[124:127], v1, s[50:51] offset:256
	global_load_dwordx4 v[128:131], v1, s[52:53] offset:256
	global_load_dwordx4 v[132:135], v1, s[58:59] offset:256
	global_load_dwordx4 v[136:139], v1, s[54:55] offset:256
	s_mov_b64 exec, -1
	s_add_u32 vcc_lo, s24, 0x10e47000
	s_addc_u32 vcc_hi, s25, 0
	s_waitcnt lgkmcnt(11)
	global_store_dwordx4 v11, v[148:151], vcc offset:0
	s_waitcnt lgkmcnt(10)
	global_store_dwordx4 v32, v[152:155], vcc offset:0
	s_add_u32 vcc_lo, s24, 0x11e47000
	s_addc_u32 vcc_hi, s25, 0
	s_waitcnt lgkmcnt(9)
	global_store_dwordx4 v11, v[156:159], vcc offset:0
	s_waitcnt lgkmcnt(8)
	global_store_dwordx4 v32, v[160:163], vcc offset:0
	s_add_u32 vcc_lo, s24, 0x12e47000
	s_addc_u32 vcc_hi, s25, 0
	s_waitcnt lgkmcnt(7)
	global_store_dwordx4 v11, v[204:207], vcc offset:0
	s_waitcnt lgkmcnt(6)
	global_store_dwordx4 v32, v[208:211], vcc offset:0
	s_add_u32 vcc_lo, s24, 0x13e47000
	s_addc_u32 vcc_hi, s25, 0
	s_waitcnt lgkmcnt(5)
	global_store_dwordx4 v11, v[212:215], vcc offset:0
	s_waitcnt lgkmcnt(4)
	global_store_dwordx4 v32, v[216:219], vcc offset:0
	s_add_u32 vcc_lo, s24, 0x14e47000
	s_addc_u32 vcc_hi, s25, 0
	s_waitcnt lgkmcnt(3)
	global_store_dwordx4 v11, v[164:167], vcc offset:0
	s_waitcnt lgkmcnt(2)
	global_store_dwordx4 v32, v[168:171], vcc offset:0
	s_add_u32 vcc_lo, s24, 0x15e47000
	s_addc_u32 vcc_hi, s25, 0
	s_waitcnt lgkmcnt(1)
	global_store_dwordx4 v11, v[172:175], vcc offset:0
	s_waitcnt lgkmcnt(0)
	global_store_dwordx4 v32, v[220:223], vcc offset:0
	s_waitcnt vmcnt(28)
	v_mov_b32_dpp v44, v44 row_newbcast:0 row_mask:0xf bank_mask:0xf
	v_mov_b32_dpp v45, v45 row_newbcast:0 row_mask:0xf bank_mask:0xf
	v_mov_b32_dpp v46, v46 row_newbcast:0 row_mask:0xf bank_mask:0xf
	v_mov_b32_dpp v47, v47 row_newbcast:0 row_mask:0xf bank_mask:0xf
	v_mov_b32_dpp v48, v48 row_newbcast:0 row_mask:0xf bank_mask:0xf
	v_mov_b32_dpp v49, v49 row_newbcast:0 row_mask:0xf bank_mask:0xf
	v_mov_b32_dpp v50, v50 row_newbcast:0 row_mask:0xf bank_mask:0xf
	v_mov_b32_dpp v51, v51 row_newbcast:0 row_mask:0xf bank_mask:0xf
	v_and_b32_e32 v42, v5, v42
	v_and_b32_e32 v43, v5, v43
	v_lshlrev_b32_e32 v204, 16, v40
	v_and_b32_e32 v205, 0xffff0000, v40
	v_lshlrev_b32_e32 v220, 16, v42
	v_and_b32_e32 v221, 0xffff0000, v42
	v_sub_f32_e32 v220, v220, v204
	v_sub_f32_e32 v221, v221, v205
	v_fmac_f32_e32 v204, v44, v220
	v_fmac_f32_e32 v205, v45, v221
	v_lshlrev_b32_e32 v206, 16, v41
	v_and_b32_e32 v207, 0xffff0000, v41
	v_lshlrev_b32_e32 v220, 16, v43
	v_and_b32_e32 v221, 0xffff0000, v43
	v_sub_f32_e32 v220, v220, v206
	v_sub_f32_e32 v221, v221, v207
	v_fmac_f32_e32 v206, v46, v220
	v_fmac_f32_e32 v207, v47, v221
	v_mul_f32_e32 v148, v204, v48
	v_mul_f32_e32 v149, v205, v49
	v_mul_f32_e32 v150, v206, v50
	v_mul_f32_e32 v151, v207, v51
	v_mul_f32_e32 v223, v148, v148
	v_fma_f32 v223, v149, v149, v223
	v_fma_f32 v223, v150, v150, v223
	v_fma_f32 v223, v151, v151, v223
	v_mov_b32_e32 v222, v223
	v_mov_b32_dpp v56, v56 row_newbcast:0 row_mask:0xf bank_mask:0xf
	v_mov_b32_dpp v57, v57 row_newbcast:0 row_mask:0xf bank_mask:0xf
	v_mov_b32_dpp v58, v58 row_newbcast:0 row_mask:0xf bank_mask:0xf
	v_mov_b32_dpp v59, v59 row_newbcast:0 row_mask:0xf bank_mask:0xf
	v_mov_b32_dpp v60, v60 row_newbcast:0 row_mask:0xf bank_mask:0xf
	v_mov_b32_dpp v61, v61 row_newbcast:0 row_mask:0xf bank_mask:0xf
	v_mov_b32_dpp v62, v62 row_newbcast:0 row_mask:0xf bank_mask:0xf
	v_mov_b32_dpp v63, v63 row_newbcast:0 row_mask:0xf bank_mask:0xf
	v_and_b32_e32 v54, v5, v54
	v_and_b32_e32 v55, v5, v55
	v_lshlrev_b32_e32 v208, 16, v52
	v_and_b32_e32 v209, 0xffff0000, v52
	v_lshlrev_b32_e32 v220, 16, v54
	v_and_b32_e32 v221, 0xffff0000, v54
	v_sub_f32_e32 v220, v220, v208
	v_sub_f32_e32 v221, v221, v209
	v_fmac_f32_e32 v208, v56, v220
	v_fmac_f32_e32 v209, v57, v221
	v_lshlrev_b32_e32 v210, 16, v53
	v_and_b32_e32 v211, 0xffff0000, v53
	v_lshlrev_b32_e32 v220, 16, v55
	v_and_b32_e32 v221, 0xffff0000, v55
	v_sub_f32_e32 v220, v220, v210
	v_sub_f32_e32 v221, v221, v211
	v_fmac_f32_e32 v210, v58, v220
	v_fmac_f32_e32 v211, v59, v221
	v_mul_f32_e32 v152, v208, v60
	v_mul_f32_e32 v153, v209, v61
	v_mul_f32_e32 v154, v210, v62
	v_mul_f32_e32 v155, v211, v63
	v_mul_f32_e32 v223, v152, v152
	v_fma_f32 v223, v153, v153, v223
	v_fma_f32 v223, v154, v154, v223
	v_fma_f32 v223, v155, v155, v223
	v_add_f32_e32 v222, v222, v223
	v_mov_b32_dpp v68, v68 row_newbcast:0 row_mask:0xf bank_mask:0xf
	v_mov_b32_dpp v69, v69 row_newbcast:0 row_mask:0xf bank_mask:0xf
	v_mov_b32_dpp v70, v70 row_newbcast:0 row_mask:0xf bank_mask:0xf
	v_mov_b32_dpp v71, v71 row_newbcast:0 row_mask:0xf bank_mask:0xf
	v_mov_b32_dpp v72, v72 row_newbcast:0 row_mask:0xf bank_mask:0xf
	v_mov_b32_dpp v73, v73 row_newbcast:0 row_mask:0xf bank_mask:0xf
	v_mov_b32_dpp v74, v74 row_newbcast:0 row_mask:0xf bank_mask:0xf
	v_mov_b32_dpp v75, v75 row_newbcast:0 row_mask:0xf bank_mask:0xf
	v_and_b32_e32 v66, v5, v66
	v_and_b32_e32 v67, v5, v67
	v_lshlrev_b32_e32 v212, 16, v64
	v_and_b32_e32 v213, 0xffff0000, v64
	v_lshlrev_b32_e32 v220, 16, v66
	v_and_b32_e32 v221, 0xffff0000, v66
	v_sub_f32_e32 v220, v220, v212
	v_sub_f32_e32 v221, v221, v213
	v_fmac_f32_e32 v212, v68, v220
	v_fmac_f32_e32 v213, v69, v221
	v_lshlrev_b32_e32 v214, 16, v65
	v_and_b32_e32 v215, 0xffff0000, v65
	v_lshlrev_b32_e32 v220, 16, v67
	v_and_b32_e32 v221, 0xffff0000, v67
	v_sub_f32_e32 v220, v220, v214
	v_sub_f32_e32 v221, v221, v215
	v_fmac_f32_e32 v214, v70, v220
	v_fmac_f32_e32 v215, v71, v221
	v_mul_f32_e32 v156, v212, v72
	v_mul_f32_e32 v157, v213, v73
	v_mul_f32_e32 v158, v214, v74
	v_mul_f32_e32 v159, v215, v75
	v_mul_f32_e32 v223, v156, v156
	v_fma_f32 v223, v157, v157, v223
	v_fma_f32 v223, v158, v158, v223
	v_fma_f32 v223, v159, v159, v223
	v_add_f32_e32 v222, v222, v223
	v_mov_b32_dpp v80, v80 row_newbcast:0 row_mask:0xf bank_mask:0xf
	v_mov_b32_dpp v81, v81 row_newbcast:0 row_mask:0xf bank_mask:0xf
	v_mov_b32_dpp v82, v82 row_newbcast:0 row_mask:0xf bank_mask:0xf
	v_mov_b32_dpp v83, v83 row_newbcast:0 row_mask:0xf bank_mask:0xf
	v_mov_b32_dpp v84, v84 row_newbcast:0 row_mask:0xf bank_mask:0xf
	v_mov_b32_dpp v85, v85 row_newbcast:0 row_mask:0xf bank_mask:0xf
	v_mov_b32_dpp v86, v86 row_newbcast:0 row_mask:0xf bank_mask:0xf
	v_mov_b32_dpp v87, v87 row_newbcast:0 row_mask:0xf bank_mask:0xf
	v_and_b32_e32 v78, v5, v78
	v_and_b32_e32 v79, v5, v79
	v_lshlrev_b32_e32 v216, 16, v76
	v_and_b32_e32 v217, 0xffff0000, v76
	v_lshlrev_b32_e32 v220, 16, v78
	v_and_b32_e32 v221, 0xffff0000, v78
	v_sub_f32_e32 v220, v220, v216
	v_sub_f32_e32 v221, v221, v217
	v_fmac_f32_e32 v216, v80, v220
	v_fmac_f32_e32 v217, v81, v221
	v_lshlrev_b32_e32 v218, 16, v77
	v_and_b32_e32 v219, 0xffff0000, v77
	v_lshlrev_b32_e32 v220, 16, v79
	v_and_b32_e32 v221, 0xffff0000, v79
	v_sub_f32_e32 v220, v220, v218
	v_sub_f32_e32 v221, v221, v219
	v_fmac_f32_e32 v218, v82, v220
	v_fmac_f32_e32 v219, v83, v221
	v_mul_f32_e32 v160, v216, v84
	v_mul_f32_e32 v161, v217, v85
	v_mul_f32_e32 v162, v218, v86
	v_mul_f32_e32 v163, v219, v87
	v_mul_f32_e32 v223, v160, v160
	v_fma_f32 v223, v161, v161, v223
	v_fma_f32 v223, v162, v162, v223
	v_fma_f32 v223, v163, v163, v223
	v_add_f32_e32 v222, v222, v223
	v_mov_b32_e32 v223, v222
	s_nop 1
	v_permlane16_swap_b32_e32 v222, v223
	s_nop 1
	v_add_f32_e32 v222, v222, v223
	v_mov_b32_e32 v223, v222
	s_nop 1
	v_permlane32_swap_b32_e32 v222, v223
	s_nop 1
	v_add_f32_e32 v222, v222, v223
	s_mov_b32 s34, 0xf800000
	v_cmp_gt_f32_e32 vcc, s34, v222
	v_mul_f32_e32 v220, 0x4f800000, v222
	s_nop 0
	v_cndmask_b32_e32 v222, v222, v220, vcc
	v_sqrt_f32_e32 v224, v222
	s_nop 0
	v_add_u32_e32 v225, -1, v224
	v_fma_f32 v226, -v225, v224, v222
	v_cmp_ge_f32_e64 s[62:63], 0, v226
	v_add_u32_e32 v227, 1, v224
	s_nop 0
	v_cndmask_b32_e64 v225, v224, v225, s[62:63]
	v_fma_f32 v226, -v227, v224, v222
	v_cmp_lt_f32_e64 s[62:63], 0, v226
	s_nop 1
	v_cndmask_b32_e64 v224, v225, v227, s[62:63]
	v_mul_f32_e32 v220, 0x37800000, v224
	v_cndmask_b32_e32 v224, v224, v220, vcc
	v_cmp_class_f32_e32 vcc, v222, v193
	s_nop 1
	v_cndmask_b32_e32 v222, v224, v222, vcc
	v_max_f32_e32 v222, 0x2b8cbccc, v222
	v_div_scale_f32 v224, s[62:63], v222, v222, 1.0
	v_rcp_f32_e32 v225, v224
	s_nop 0
	v_fma_f32 v226, -v224, v225, 1.0
	v_fmac_f32_e32 v225, v226, v225
	v_div_scale_f32 v227, vcc, 1.0, v222, 1.0
	v_mul_f32_e32 v220, v227, v225
	v_fma_f32 v221, -v224, v220, v227
	v_fmac_f32_e32 v220, v221, v225
	v_fma_f32 v224, -v224, v220, v227
	s_nop 1
	v_div_fmas_f32 v224, v224, v225, v220
	v_div_fixup_f32 v34, v224, v222, 1.0
	global_load_dwordx2 v[40:41], v2, s[40:41] offset:160
	global_load_dwordx2 v[42:43], v2, s[42:43] offset:160
	global_load_dwordx2 v[48:49], v2, s[40:41] offset:2208
	global_load_dwordx2 v[50:51], v2, s[42:43] offset:2208
	global_load_dwordx4 v[56:59], v176, s[60:61] offset:2048
	global_load_dwordx4 v[60:63], v176, s[60:61] offset:2112
	global_load_dwordx4 v[64:67], v182, s[60:61] offset:2048
	global_load_dwordx4 v[68:71], v182, s[60:61] offset:2112
	global_load_dwordx4 v[72:75], v181, s[100:101] offset:1024
	global_load_dwordx2 v[146:147], v8, s[0:1] offset:160
	s_mov_b32 exec_lo, 0x10001
	s_mov_b32 exec_hi, 0x10001
	global_load_dwordx4 v[44:47], v1, s[46:47] offset:-1728
	global_load_dwordx4 v[52:55], v1, s[46:47] offset:2368
	global_load_dwordx4 v[76:79], v1, s[50:51] offset:320
	global_load_dwordx4 v[80:83], v1, s[52:53] offset:320
	global_load_dwordx4 v[84:87], v1, s[58:59] offset:320
	global_load_dwordx4 v[142:145], v1, s[54:55] offset:320
	s_mov_b64 exec, -1
	s_waitcnt vmcnt(28)
	v_mov_b32_dpp v92, v92 row_newbcast:0 row_mask:0xf bank_mask:0xf
	v_mov_b32_dpp v93, v93 row_newbcast:0 row_mask:0xf bank_mask:0xf
	v_mov_b32_dpp v94, v94 row_newbcast:0 row_mask:0xf bank_mask:0xf
	v_mov_b32_dpp v95, v95 row_newbcast:0 row_mask:0xf bank_mask:0xf
	v_mov_b32_dpp v100, v100 row_newbcast:0 row_mask:0xf bank_mask:0xf
	v_mov_b32_dpp v101, v101 row_newbcast:0 row_mask:0xf bank_mask:0xf
	v_mov_b32_dpp v102, v102 row_newbcast:0 row_mask:0xf bank_mask:0xf
	v_mov_b32_dpp v103, v103 row_newbcast:0 row_mask:0xf bank_mask:0xf
	v_mov_b32_dpp v124, v124 row_newbcast:0 row_mask:0xf bank_mask:0xf
	v_mov_b32_dpp v125, v125 row_newbcast:0 row_mask:0xf bank_mask:0xf
	v_mov_b32_dpp v126, v126 row_newbcast:0 row_mask:0xf bank_mask:0xf
	v_mov_b32_dpp v127, v127 row_newbcast:0 row_mask:0xf bank_mask:0xf
	v_mov_b32_dpp v128, v128 row_newbcast:0 row_mask:0xf bank_mask:0xf
	v_mov_b32_dpp v129, v129 row_newbcast:0 row_mask:0xf bank_mask:0xf
	v_mov_b32_dpp v130, v130 row_newbcast:0 row_mask:0xf bank_mask:0xf
	v_mov_b32_dpp v131, v131 row_newbcast:0 row_mask:0xf bank_mask:0xf
	v_mov_b32_dpp v132, v132 row_newbcast:0 row_mask:0xf bank_mask:0xf
	v_mov_b32_dpp v133, v133 row_newbcast:0 row_mask:0xf bank_mask:0xf
	v_mov_b32_dpp v134, v134 row_newbcast:0 row_mask:0xf bank_mask:0xf
	v_mov_b32_dpp v135, v135 row_newbcast:0 row_mask:0xf bank_mask:0xf
	v_mov_b32_dpp v136, v136 row_newbcast:0 row_mask:0xf bank_mask:0xf
	v_mov_b32_dpp v137, v137 row_newbcast:0 row_mask:0xf bank_mask:0xf
	v_mov_b32_dpp v138, v138 row_newbcast:0 row_mask:0xf bank_mask:0xf
	v_mov_b32_dpp v139, v139 row_newbcast:0 row_mask:0xf bank_mask:0xf
	s_nop 1
	v_mfma_f32_16x16x32_bf16 v[164:167], v[104:107], v[12:15], 0
	v_mfma_f32_16x16x32_bf16 v[168:171], v[112:115], v[20:23], 0
	v_mfma_f32_16x16x32_bf16 v[172:175], v[120:123], v[28:31], 0
	v_mfma_f32_16x16x32_bf16 v[164:167], v[108:111], v[16:19], v[164:167]
	v_mfma_f32_16x16x32_bf16 v[168:171], v[116:119], v[24:27], v[168:171]
	v_and_b32_e32 v90, v5, v90
	v_and_b32_e32 v91, v5, v91
	v_lshlrev_b32_e32 v184, 16, v88
	v_and_b32_e32 v185, 0xffff0000, v88
	v_lshlrev_b32_e32 v220, 16, v90
	v_and_b32_e32 v221, 0xffff0000, v90
	v_sub_f32_e32 v220, v220, v184
	v_sub_f32_e32 v221, v221, v185
	v_fmac_f32_e32 v184, v92, v220
	v_fmac_f32_e32 v185, v93, v221
	v_lshlrev_b32_e32 v186, 16, v89
	v_and_b32_e32 v187, 0xffff0000, v89
	v_lshlrev_b32_e32 v220, 16, v91
	v_and_b32_e32 v221, 0xffff0000, v91
	v_sub_f32_e32 v220, v220, v186
	v_sub_f32_e32 v221, v221, v187
	v_fmac_f32_e32 v186, v94, v220
	v_fmac_f32_e32 v187, v95, v221
	v_and_b32_e32 v98, v5, v98
	v_and_b32_e32 v99, v5, v99
	v_lshlrev_b32_e32 v228, 16, v96
	v_and_b32_e32 v229, 0xffff0000, v96
	v_lshlrev_b32_e32 v220, 16, v98
	v_and_b32_e32 v221, 0xffff0000, v98
	v_sub_f32_e32 v220, v220, v228
	v_sub_f32_e32 v221, v221, v229
	v_fmac_f32_e32 v228, v100, v220
	v_fmac_f32_e32 v229, v101, v221
	v_lshlrev_b32_e32 v230, 16, v97
	v_and_b32_e32 v231, 0xffff0000, v97
	v_lshlrev_b32_e32 v220, 16, v99
	v_and_b32_e32 v221, 0xffff0000, v99
	v_sub_f32_e32 v220, v220, v230
	v_sub_f32_e32 v221, v221, v231
	v_fmac_f32_e32 v230, v102, v220
	v_fmac_f32_e32 v231, v103, v221
	s_nop 7
	v_add_f32_e32 v164, v124, v164
	v_add_f32_e32 v168, v128, v168
	v_add_f32_e32 v172, v136, v172
	v_add_f32_e32 v165, v125, v165
	v_add_f32_e32 v169, v129, v169
	v_add_f32_e32 v173, v137, v173
	v_add_f32_e32 v166, v126, v166
	v_add_f32_e32 v170, v130, v170
	v_add_f32_e32 v174, v138, v174
	v_add_f32_e32 v167, v127, v167
	v_add_f32_e32 v171, v131, v171
	v_add_f32_e32 v175, v139, v175
	v_mul_f32_e32 v164, 0xbfb8aa3b, v164
	v_exp_f32_e32 v164, v164
	s_nop 0
	v_add_f32_e32 v164, 1.0, v164
	v_rcp_f32_e32 v164, v164
	v_mul_f32_e32 v168, 0xbfb8aa3b, v168
	v_exp_f32_e32 v168, v168
	s_nop 0
	v_add_f32_e32 v168, 1.0, v168
	v_rcp_f32_e32 v168, v168
	v_mul_f32_e32 v172, 0xbfb8aa3b, v172
	v_exp_f32_e32 v172, v172
	s_nop 0
	v_add_f32_e32 v172, 1.0, v172
	v_rcp_f32_e32 v172, v172
	v_mul_f32_e32 v165, 0xbfb8aa3b, v165
	v_exp_f32_e32 v165, v165
	s_nop 0
	v_add_f32_e32 v165, 1.0, v165
	v_rcp_f32_e32 v165, v165
	v_mul_f32_e32 v169, 0xbfb8aa3b, v169
	v_exp_f32_e32 v169, v169
	s_nop 0
	v_add_f32_e32 v169, 1.0, v169
	v_rcp_f32_e32 v169, v169
	v_mul_f32_e32 v173, 0xbfb8aa3b, v173
	v_exp_f32_e32 v173, v173
	s_nop 0
	v_add_f32_e32 v173, 1.0, v173
	v_rcp_f32_e32 v173, v173
	v_mul_f32_e32 v166, 0xbfb8aa3b, v166
	v_exp_f32_e32 v166, v166
	s_nop 0
	v_add_f32_e32 v166, 1.0, v166
	v_rcp_f32_e32 v166, v166
	v_mul_f32_e32 v170, 0xbfb8aa3b, v170
	v_exp_f32_e32 v170, v170
	s_nop 0
	v_add_f32_e32 v170, 1.0, v170
	v_rcp_f32_e32 v170, v170
	v_mul_f32_e32 v174, 0xbfb8aa3b, v174
	v_exp_f32_e32 v174, v174
	s_nop 0
	v_add_f32_e32 v174, 1.0, v174
	v_rcp_f32_e32 v174, v174
	v_mul_f32_e32 v167, 0xbfb8aa3b, v167
	v_exp_f32_e32 v167, v167
	s_nop 0
	v_add_f32_e32 v167, 1.0, v167
	v_rcp_f32_e32 v167, v167
	v_mul_f32_e32 v171, 0xbfb8aa3b, v171
	v_exp_f32_e32 v171, v171
	s_nop 0
	v_add_f32_e32 v171, 1.0, v171
	v_rcp_f32_e32 v171, v171
	v_mul_f32_e32 v175, 0xbfb8aa3b, v175
	v_exp_f32_e32 v175, v175
	s_nop 0
	v_add_f32_e32 v175, 1.0, v175
	v_rcp_f32_e32 v175, v175
	v_mul_f32_e32 v164, 0x3f1b4598, v164
	v_mul_f32_e32 v165, 0x3f1b4598, v165
	v_mul_f32_e32 v166, 0x3f1b4598, v166
	v_mul_f32_e32 v167, 0x3f1b4598, v167
	s_cmp_eq_u32 s32, 0
	s_cbranch_scc1 .Lprep2_l0_1_0
	v_lshlrev_b32_e32 v220, 16, v140
	v_and_b32_e32 v221, 0xffff0000, v140
	v_lshlrev_b32_e32 v222, 16, v141
	v_and_b32_e32 v223, 0xffff0000, v141
	v_sub_f32_e32 v220, v220, v228
	v_fmac_f32_e32 v228, v220, v172
	v_sub_f32_e32 v221, v221, v229
	v_fmac_f32_e32 v229, v221, v173
	v_sub_f32_e32 v222, v222, v230
	v_fmac_f32_e32 v230, v222, v174
	v_sub_f32_e32 v223, v223, v231
	v_fmac_f32_e32 v231, v223, v175
	s_branch .Lprep2_l0d_1_0

.Lprep2_l0d_1_0:
	global_store_dwordx2 v8, v[140:141], s[0:1] offset:128
	v_mul_f32_e32 v220, v148, v34
	v_mul_f32_e32 v224, v220, v168
	v_add_f32_e32 v168, -1.0, v168
	v_fma_f32 v168, v168, v132, 1.0
	v_mul_f32_e32 v168, v204, v168
	v_mul_f32_e32 v221, v149, v34
	v_mul_f32_e32 v225, v221, v169
	v_add_f32_e32 v169, -1.0, v169
	v_fma_f32 v169, v169, v133, 1.0
	v_mul_f32_e32 v169, v205, v169
	v_mul_f32_e32 v222, v150, v34
	v_mul_f32_e32 v226, v222, v170
	v_add_f32_e32 v170, -1.0, v170
	v_fma_f32 v170, v170, v134, 1.0
	v_mul_f32_e32 v170, v206, v170
	v_mul_f32_e32 v223, v151, v34
	v_mul_f32_e32 v227, v223, v171
	v_add_f32_e32 v171, -1.0, v171
	v_fma_f32 v171, v171, v135, 1.0
	v_mul_f32_e32 v171, v207, v171
	v_cvt_pk_bf16_f32 v88, v184, v185
	v_cvt_pk_bf16_f32 v89, v186, v187
	ds_write_b64 v9, v[88:89] offset:0
	v_cvt_pk_bf16_f32 v88, v168, v169
	v_cvt_pk_bf16_f32 v89, v170, v171
	ds_write_b64 v9, v[88:89] offset:2304
	v_cvt_pk_bf16_f32 v88, v228, v229
	v_cvt_pk_bf16_f32 v89, v230, v231
	ds_write_b64 v9, v[88:89] offset:4608
	v_cvt_pk_bf16_f32 v88, v220, v221
	v_cvt_pk_bf16_f32 v89, v222, v223
	ds_write_b64 v9, v[88:89] offset:6912
	v_cvt_pk_bf16_f32 v88, v224, v225
	v_cvt_pk_bf16_f32 v89, v226, v227
	ds_write_b64 v9, v[88:89] offset:9216
	v_cvt_pk_bf16_f32 v88, v164, v165
	v_cvt_pk_bf16_f32 v89, v166, v167
	ds_write_b64 v9, v[88:89] offset:11520
	global_load_dwordx2 v[88:89], v2, s[40:41] offset:192
	global_load_dwordx2 v[90:91], v2, s[42:43] offset:192
	global_load_dwordx2 v[96:97], v2, s[40:41] offset:2240
	global_load_dwordx2 v[98:99], v2, s[42:43] offset:2240
	global_load_dwordx4 v[104:107], v177, s[60:61] offset:0
	global_load_dwordx4 v[108:111], v177, s[60:61] offset:64
	global_load_dwordx4 v[112:115], v183, s[60:61] offset:0
	global_load_dwordx4 v[116:119], v183, s[60:61] offset:64
	global_load_dwordx4 v[120:123], v181, s[100:101] offset:2048
	global_load_dwordx2 v[140:141], v8, s[0:1] offset:192
	s_mov_b32 exec_lo, 0x10001
	s_mov_b32 exec_hi, 0x10001
	global_load_dwordx4 v[92:95], v1, s[46:47] offset:-1664
	global_load_dwordx4 v[100:103], v1, s[46:47] offset:2432
	global_load_dwordx4 v[124:127], v1, s[50:51] offset:384
	global_load_dwordx4 v[128:131], v1, s[52:53] offset:384
	global_load_dwordx4 v[132:135], v1, s[58:59] offset:384
	global_load_dwordx4 v[136:139], v1, s[54:55] offset:384
	s_mov_b64 exec, -1
	s_waitcnt vmcnt(17)
	v_mov_b32_dpp v44, v44 row_newbcast:0 row_mask:0xf bank_mask:0xf
	v_mov_b32_dpp v45, v45 row_newbcast:0 row_mask:0xf bank_mask:0xf
	v_mov_b32_dpp v46, v46 row_newbcast:0 row_mask:0xf bank_mask:0xf
	v_mov_b32_dpp v47, v47 row_newbcast:0 row_mask:0xf bank_mask:0xf
	v_mov_b32_dpp v52, v52 row_newbcast:0 row_mask:0xf bank_mask:0xf
	v_mov_b32_dpp v53, v53 row_newbcast:0 row_mask:0xf bank_mask:0xf
	v_mov_b32_dpp v54, v54 row_newbcast:0 row_mask:0xf bank_mask:0xf
	v_mov_b32_dpp v55, v55 row_newbcast:0 row_mask:0xf bank_mask:0xf
	v_mov_b32_dpp v76, v76 row_newbcast:0 row_mask:0xf bank_mask:0xf
	v_mov_b32_dpp v77, v77 row_newbcast:0 row_mask:0xf bank_mask:0xf
	v_mov_b32_dpp v78, v78 row_newbcast:0 row_mask:0xf bank_mask:0xf
	v_mov_b32_dpp v79, v79 row_newbcast:0 row_mask:0xf bank_mask:0xf
	v_mov_b32_dpp v80, v80 row_newbcast:0 row_mask:0xf bank_mask:0xf
	v_mov_b32_dpp v81, v81 row_newbcast:0 row_mask:0xf bank_mask:0xf
	v_mov_b32_dpp v82, v82 row_newbcast:0 row_mask:0xf bank_mask:0xf
	v_mov_b32_dpp v83, v83 row_newbcast:0 row_mask:0xf bank_mask:0xf
	v_mov_b32_dpp v84, v84 row_newbcast:0 row_mask:0xf bank_mask:0xf
	v_mov_b32_dpp v85, v85 row_newbcast:0 row_mask:0xf bank_mask:0xf
	v_mov_b32_dpp v86, v86 row_newbcast:0 row_mask:0xf bank_mask:0xf
	v_mov_b32_dpp v87, v87 row_newbcast:0 row_mask:0xf bank_mask:0xf
	v_mov_b32_dpp v142, v142 row_newbcast:0 row_mask:0xf bank_mask:0xf
	v_mov_b32_dpp v143, v143 row_newbcast:0 row_mask:0xf bank_mask:0xf
	v_mov_b32_dpp v144, v144 row_newbcast:0 row_mask:0xf bank_mask:0xf
	v_mov_b32_dpp v145, v145 row_newbcast:0 row_mask:0xf bank_mask:0xf
	s_nop 1
	v_mfma_f32_16x16x32_bf16 v[164:167], v[56:59], v[12:15], 0
	v_mfma_f32_16x16x32_bf16 v[168:171], v[64:67], v[20:23], 0
	v_mfma_f32_16x16x32_bf16 v[172:175], v[72:75], v[28:31], 0
	v_mfma_f32_16x16x32_bf16 v[164:167], v[60:63], v[16:19], v[164:167]
	v_mfma_f32_16x16x32_bf16 v[168:171], v[68:71], v[24:27], v[168:171]
	v_and_b32_e32 v42, v5, v42
	v_and_b32_e32 v43, v5, v43
	v_lshlrev_b32_e32 v184, 16, v40
	v_and_b32_e32 v185, 0xffff0000, v40
	v_lshlrev_b32_e32 v220, 16, v42
	v_and_b32_e32 v221, 0xffff0000, v42
	v_sub_f32_e32 v220, v220, v184
	v_sub_f32_e32 v221, v221, v185
	v_fmac_f32_e32 v184, v44, v220
	v_fmac_f32_e32 v185, v45, v221
	v_lshlrev_b32_e32 v186, 16, v41
	v_and_b32_e32 v187, 0xffff0000, v41
	v_lshlrev_b32_e32 v220, 16, v43
	v_and_b32_e32 v221, 0xffff0000, v43
	v_sub_f32_e32 v220, v220, v186
	v_sub_f32_e32 v221, v221, v187
	v_fmac_f32_e32 v186, v46, v220
	v_fmac_f32_e32 v187, v47, v221
	v_and_b32_e32 v50, v5, v50
	v_and_b32_e32 v51, v5, v51
	v_lshlrev_b32_e32 v228, 16, v48
	v_and_b32_e32 v229, 0xffff0000, v48
	v_lshlrev_b32_e32 v220, 16, v50
	v_and_b32_e32 v221, 0xffff0000, v50
	v_sub_f32_e32 v220, v220, v228
	v_sub_f32_e32 v221, v221, v229
	v_fmac_f32_e32 v228, v52, v220
	v_fmac_f32_e32 v229, v53, v221
	v_lshlrev_b32_e32 v230, 16, v49
	v_and_b32_e32 v231, 0xffff0000, v49
	v_lshlrev_b32_e32 v220, 16, v51
	v_and_b32_e32 v221, 0xffff0000, v51
	v_sub_f32_e32 v220, v220, v230
	v_sub_f32_e32 v221, v221, v231
	v_fmac_f32_e32 v230, v54, v220
	v_fmac_f32_e32 v231, v55, v221
	s_nop 7
	v_add_f32_e32 v164, v76, v164
	v_add_f32_e32 v168, v80, v168
	v_add_f32_e32 v172, v142, v172
	v_add_f32_e32 v165, v77, v165
	v_add_f32_e32 v169, v81, v169
	v_add_f32_e32 v173, v143, v173
	v_add_f32_e32 v166, v78, v166
	v_add_f32_e32 v170, v82, v170
	v_add_f32_e32 v174, v144, v174
	v_add_f32_e32 v167, v79, v167
	v_add_f32_e32 v171, v83, v171
	v_add_f32_e32 v175, v145, v175
	v_mul_f32_e32 v164, 0xbfb8aa3b, v164
	v_exp_f32_e32 v164, v164
	s_nop 0
	v_add_f32_e32 v164, 1.0, v164
	v_rcp_f32_e32 v164, v164
	v_mul_f32_e32 v168, 0xbfb8aa3b, v168
	v_exp_f32_e32 v168, v168
	s_nop 0
	v_add_f32_e32 v168, 1.0, v168
	v_rcp_f32_e32 v168, v168
	v_mul_f32_e32 v172, 0xbfb8aa3b, v172
	v_exp_f32_e32 v172, v172
	s_nop 0
	v_add_f32_e32 v172, 1.0, v172
	v_rcp_f32_e32 v172, v172
	v_mul_f32_e32 v165, 0xbfb8aa3b, v165
	v_exp_f32_e32 v165, v165
	s_nop 0
	v_add_f32_e32 v165, 1.0, v165
	v_rcp_f32_e32 v165, v165
	v_mul_f32_e32 v169, 0xbfb8aa3b, v169
	v_exp_f32_e32 v169, v169
	s_nop 0
	v_add_f32_e32 v169, 1.0, v169
	v_rcp_f32_e32 v169, v169
	v_mul_f32_e32 v173, 0xbfb8aa3b, v173
	v_exp_f32_e32 v173, v173
	s_nop 0
	v_add_f32_e32 v173, 1.0, v173
	v_rcp_f32_e32 v173, v173
	v_mul_f32_e32 v166, 0xbfb8aa3b, v166
	v_exp_f32_e32 v166, v166
	s_nop 0
	v_add_f32_e32 v166, 1.0, v166
	v_rcp_f32_e32 v166, v166
	v_mul_f32_e32 v170, 0xbfb8aa3b, v170
	v_exp_f32_e32 v170, v170
	s_nop 0
	v_add_f32_e32 v170, 1.0, v170
	v_rcp_f32_e32 v170, v170
	v_mul_f32_e32 v174, 0xbfb8aa3b, v174
	v_exp_f32_e32 v174, v174
	s_nop 0
	v_add_f32_e32 v174, 1.0, v174
	v_rcp_f32_e32 v174, v174
	v_mul_f32_e32 v167, 0xbfb8aa3b, v167
	v_exp_f32_e32 v167, v167
	s_nop 0
	v_add_f32_e32 v167, 1.0, v167
	v_rcp_f32_e32 v167, v167
	v_mul_f32_e32 v171, 0xbfb8aa3b, v171
	v_exp_f32_e32 v171, v171
	s_nop 0
	v_add_f32_e32 v171, 1.0, v171
	v_rcp_f32_e32 v171, v171
	v_mul_f32_e32 v175, 0xbfb8aa3b, v175
	v_exp_f32_e32 v175, v175
	s_nop 0
	v_add_f32_e32 v175, 1.0, v175
	v_rcp_f32_e32 v175, v175
	v_mul_f32_e32 v164, 0x3f1b4598, v164
	v_mul_f32_e32 v165, 0x3f1b4598, v165
	v_mul_f32_e32 v166, 0x3f1b4598, v166
	v_mul_f32_e32 v167, 0x3f1b4598, v167
	s_cmp_eq_u32 s32, 0
	s_cbranch_scc1 .Lprep2_l0_1_1
	v_lshlrev_b32_e32 v220, 16, v146
	v_and_b32_e32 v221, 0xffff0000, v146
	v_lshlrev_b32_e32 v222, 16, v147
	v_and_b32_e32 v223, 0xffff0000, v147
	v_sub_f32_e32 v220, v220, v228
	v_fmac_f32_e32 v228, v220, v172
	v_sub_f32_e32 v221, v221, v229
	v_fmac_f32_e32 v229, v221, v173
	v_sub_f32_e32 v222, v222, v230
	v_fmac_f32_e32 v230, v222, v174
	v_sub_f32_e32 v223, v223, v231
	v_fmac_f32_e32 v231, v223, v175
	s_branch .Lprep2_l0d_1_1

.Lprep2_l0d_1_1:
	global_store_dwordx2 v8, v[146:147], s[0:1] offset:160
	v_mul_f32_e32 v220, v152, v34
	v_mul_f32_e32 v224, v220, v168
	v_add_f32_e32 v168, -1.0, v168
	v_fma_f32 v168, v168, v84, 1.0
	v_mul_f32_e32 v168, v208, v168
	v_mul_f32_e32 v221, v153, v34
	v_mul_f32_e32 v225, v221, v169
	v_add_f32_e32 v169, -1.0, v169
	v_fma_f32 v169, v169, v85, 1.0
	v_mul_f32_e32 v169, v209, v169
	v_mul_f32_e32 v222, v154, v34
	v_mul_f32_e32 v226, v222, v170
	v_add_f32_e32 v170, -1.0, v170
	v_fma_f32 v170, v170, v86, 1.0
	v_mul_f32_e32 v170, v210, v170
	v_mul_f32_e32 v223, v155, v34
	v_mul_f32_e32 v227, v223, v171
	v_add_f32_e32 v171, -1.0, v171
	v_fma_f32 v171, v171, v87, 1.0
	v_mul_f32_e32 v171, v211, v171
	v_cvt_pk_bf16_f32 v40, v184, v185
	v_cvt_pk_bf16_f32 v41, v186, v187
	ds_write_b64 v9, v[40:41] offset:32
	v_cvt_pk_bf16_f32 v40, v168, v169
	v_cvt_pk_bf16_f32 v41, v170, v171
	ds_write_b64 v9, v[40:41] offset:2336
	v_cvt_pk_bf16_f32 v40, v228, v229
	v_cvt_pk_bf16_f32 v41, v230, v231
	ds_write_b64 v9, v[40:41] offset:4640
	v_cvt_pk_bf16_f32 v40, v220, v221
	v_cvt_pk_bf16_f32 v41, v222, v223
	ds_write_b64 v9, v[40:41] offset:6944
	v_cvt_pk_bf16_f32 v40, v224, v225
	v_cvt_pk_bf16_f32 v41, v226, v227
	ds_write_b64 v9, v[40:41] offset:9248
	v_cvt_pk_bf16_f32 v40, v164, v165
	v_cvt_pk_bf16_f32 v41, v166, v167
	ds_write_b64 v9, v[40:41] offset:11552
	global_load_dwordx2 v[40:41], v2, s[40:41] offset:224
	global_load_dwordx2 v[42:43], v2, s[42:43] offset:224
	global_load_dwordx2 v[48:49], v2, s[40:41] offset:2272
	global_load_dwordx2 v[50:51], v2, s[42:43] offset:2272
	global_load_dwordx4 v[56:59], v177, s[60:61] offset:2048
	global_load_dwordx4 v[60:63], v177, s[60:61] offset:2112
	global_load_dwordx4 v[64:67], v183, s[60:61] offset:2048
	global_load_dwordx4 v[68:71], v183, s[60:61] offset:2112
	global_load_dwordx4 v[72:75], v181, s[100:101] offset:3072
	global_load_dwordx2 v[146:147], v8, s[0:1] offset:224
	s_mov_b32 exec_lo, 0x10001
	s_mov_b32 exec_hi, 0x10001
	global_load_dwordx4 v[44:47], v1, s[46:47] offset:-1600
	global_load_dwordx4 v[52:55], v1, s[46:47] offset:2496
	global_load_dwordx4 v[76:79], v1, s[50:51] offset:448
	global_load_dwordx4 v[80:83], v1, s[52:53] offset:448
	global_load_dwordx4 v[84:87], v1, s[58:59] offset:448
	global_load_dwordx4 v[142:145], v1, s[54:55] offset:448
	s_mov_b64 exec, -1
	s_waitcnt vmcnt(17)
	v_mov_b32_dpp v92, v92 row_newbcast:0 row_mask:0xf bank_mask:0xf
	v_mov_b32_dpp v93, v93 row_newbcast:0 row_mask:0xf bank_mask:0xf
	v_mov_b32_dpp v94, v94 row_newbcast:0 row_mask:0xf bank_mask:0xf
	v_mov_b32_dpp v95, v95 row_newbcast:0 row_mask:0xf bank_mask:0xf
	v_mov_b32_dpp v100, v100 row_newbcast:0 row_mask:0xf bank_mask:0xf
	v_mov_b32_dpp v101, v101 row_newbcast:0 row_mask:0xf bank_mask:0xf
	v_mov_b32_dpp v102, v102 row_newbcast:0 row_mask:0xf bank_mask:0xf
	v_mov_b32_dpp v103, v103 row_newbcast:0 row_mask:0xf bank_mask:0xf
	v_mov_b32_dpp v124, v124 row_newbcast:0 row_mask:0xf bank_mask:0xf
	v_mov_b32_dpp v125, v125 row_newbcast:0 row_mask:0xf bank_mask:0xf
	v_mov_b32_dpp v126, v126 row_newbcast:0 row_mask:0xf bank_mask:0xf
	v_mov_b32_dpp v127, v127 row_newbcast:0 row_mask:0xf bank_mask:0xf
	v_mov_b32_dpp v128, v128 row_newbcast:0 row_mask:0xf bank_mask:0xf
	v_mov_b32_dpp v129, v129 row_newbcast:0 row_mask:0xf bank_mask:0xf
	v_mov_b32_dpp v130, v130 row_newbcast:0 row_mask:0xf bank_mask:0xf
	v_mov_b32_dpp v131, v131 row_newbcast:0 row_mask:0xf bank_mask:0xf
	v_mov_b32_dpp v132, v132 row_newbcast:0 row_mask:0xf bank_mask:0xf
	v_mov_b32_dpp v133, v133 row_newbcast:0 row_mask:0xf bank_mask:0xf
	v_mov_b32_dpp v134, v134 row_newbcast:0 row_mask:0xf bank_mask:0xf
	v_mov_b32_dpp v135, v135 row_newbcast:0 row_mask:0xf bank_mask:0xf
	v_mov_b32_dpp v136, v136 row_newbcast:0 row_mask:0xf bank_mask:0xf
	v_mov_b32_dpp v137, v137 row_newbcast:0 row_mask:0xf bank_mask:0xf
	v_mov_b32_dpp v138, v138 row_newbcast:0 row_mask:0xf bank_mask:0xf
	v_mov_b32_dpp v139, v139 row_newbcast:0 row_mask:0xf bank_mask:0xf
	s_nop 1
	v_mfma_f32_16x16x32_bf16 v[164:167], v[104:107], v[12:15], 0
	v_mfma_f32_16x16x32_bf16 v[168:171], v[112:115], v[20:23], 0
	v_mfma_f32_16x16x32_bf16 v[172:175], v[120:123], v[28:31], 0
	v_mfma_f32_16x16x32_bf16 v[164:167], v[108:111], v[16:19], v[164:167]
	v_mfma_f32_16x16x32_bf16 v[168:171], v[116:119], v[24:27], v[168:171]
	v_and_b32_e32 v90, v5, v90
	v_and_b32_e32 v91, v5, v91
	v_lshlrev_b32_e32 v184, 16, v88
	v_and_b32_e32 v185, 0xffff0000, v88
	v_lshlrev_b32_e32 v220, 16, v90
	v_and_b32_e32 v221, 0xffff0000, v90
	v_sub_f32_e32 v220, v220, v184
	v_sub_f32_e32 v221, v221, v185
	v_fmac_f32_e32 v184, v92, v220
	v_fmac_f32_e32 v185, v93, v221
	v_lshlrev_b32_e32 v186, 16, v89
	v_and_b32_e32 v187, 0xffff0000, v89
	v_lshlrev_b32_e32 v220, 16, v91
	v_and_b32_e32 v221, 0xffff0000, v91
	v_sub_f32_e32 v220, v220, v186
	v_sub_f32_e32 v221, v221, v187
	v_fmac_f32_e32 v186, v94, v220
	v_fmac_f32_e32 v187, v95, v221
	v_and_b32_e32 v98, v5, v98
	v_and_b32_e32 v99, v5, v99
	v_lshlrev_b32_e32 v228, 16, v96
	v_and_b32_e32 v229, 0xffff0000, v96
	v_lshlrev_b32_e32 v220, 16, v98
	v_and_b32_e32 v221, 0xffff0000, v98
	v_sub_f32_e32 v220, v220, v228
	v_sub_f32_e32 v221, v221, v229
	v_fmac_f32_e32 v228, v100, v220
	v_fmac_f32_e32 v229, v101, v221
	v_lshlrev_b32_e32 v230, 16, v97
	v_and_b32_e32 v231, 0xffff0000, v97
	v_lshlrev_b32_e32 v220, 16, v99
	v_and_b32_e32 v221, 0xffff0000, v99
	v_sub_f32_e32 v220, v220, v230
	v_sub_f32_e32 v221, v221, v231
	v_fmac_f32_e32 v230, v102, v220
	v_fmac_f32_e32 v231, v103, v221
	s_nop 7
	v_add_f32_e32 v164, v124, v164
	v_add_f32_e32 v168, v128, v168
	v_add_f32_e32 v172, v136, v172
	v_add_f32_e32 v165, v125, v165
	v_add_f32_e32 v169, v129, v169
	v_add_f32_e32 v173, v137, v173
	v_add_f32_e32 v166, v126, v166
	v_add_f32_e32 v170, v130, v170
	v_add_f32_e32 v174, v138, v174
	v_add_f32_e32 v167, v127, v167
	v_add_f32_e32 v171, v131, v171
	v_add_f32_e32 v175, v139, v175
	v_mul_f32_e32 v164, 0xbfb8aa3b, v164
	v_exp_f32_e32 v164, v164
	s_nop 0
	v_add_f32_e32 v164, 1.0, v164
	v_rcp_f32_e32 v164, v164
	v_mul_f32_e32 v168, 0xbfb8aa3b, v168
	v_exp_f32_e32 v168, v168
	s_nop 0
	v_add_f32_e32 v168, 1.0, v168
	v_rcp_f32_e32 v168, v168
	v_mul_f32_e32 v172, 0xbfb8aa3b, v172
	v_exp_f32_e32 v172, v172
	s_nop 0
	v_add_f32_e32 v172, 1.0, v172
	v_rcp_f32_e32 v172, v172
	v_mul_f32_e32 v165, 0xbfb8aa3b, v165
	v_exp_f32_e32 v165, v165
	s_nop 0
	v_add_f32_e32 v165, 1.0, v165
	v_rcp_f32_e32 v165, v165
	v_mul_f32_e32 v169, 0xbfb8aa3b, v169
	v_exp_f32_e32 v169, v169
	s_nop 0
	v_add_f32_e32 v169, 1.0, v169
	v_rcp_f32_e32 v169, v169
	v_mul_f32_e32 v173, 0xbfb8aa3b, v173
	v_exp_f32_e32 v173, v173
	s_nop 0
	v_add_f32_e32 v173, 1.0, v173
	v_rcp_f32_e32 v173, v173
	v_mul_f32_e32 v166, 0xbfb8aa3b, v166
	v_exp_f32_e32 v166, v166
	s_nop 0
	v_add_f32_e32 v166, 1.0, v166
	v_rcp_f32_e32 v166, v166
	v_mul_f32_e32 v170, 0xbfb8aa3b, v170
	v_exp_f32_e32 v170, v170
	s_nop 0
	v_add_f32_e32 v170, 1.0, v170
	v_rcp_f32_e32 v170, v170
	v_mul_f32_e32 v174, 0xbfb8aa3b, v174
	v_exp_f32_e32 v174, v174
	s_nop 0
	v_add_f32_e32 v174, 1.0, v174
	v_rcp_f32_e32 v174, v174
	v_mul_f32_e32 v167, 0xbfb8aa3b, v167
	v_exp_f32_e32 v167, v167
	s_nop 0
	v_add_f32_e32 v167, 1.0, v167
	v_rcp_f32_e32 v167, v167
	v_mul_f32_e32 v171, 0xbfb8aa3b, v171
	v_exp_f32_e32 v171, v171
	s_nop 0
	v_add_f32_e32 v171, 1.0, v171
	v_rcp_f32_e32 v171, v171
	v_mul_f32_e32 v175, 0xbfb8aa3b, v175
	v_exp_f32_e32 v175, v175
	s_nop 0
	v_add_f32_e32 v175, 1.0, v175
	v_rcp_f32_e32 v175, v175
	v_mul_f32_e32 v164, 0x3f1b4598, v164
	v_mul_f32_e32 v165, 0x3f1b4598, v165
	v_mul_f32_e32 v166, 0x3f1b4598, v166
	v_mul_f32_e32 v167, 0x3f1b4598, v167
	s_cmp_eq_u32 s32, 0
	s_cbranch_scc1 .Lprep2_l0_1_2
	v_lshlrev_b32_e32 v220, 16, v140
	v_and_b32_e32 v221, 0xffff0000, v140
	v_lshlrev_b32_e32 v222, 16, v141
	v_and_b32_e32 v223, 0xffff0000, v141
	v_sub_f32_e32 v220, v220, v228
	v_fmac_f32_e32 v228, v220, v172
	v_sub_f32_e32 v221, v221, v229
	v_fmac_f32_e32 v229, v221, v173
	v_sub_f32_e32 v222, v222, v230
	v_fmac_f32_e32 v230, v222, v174
	v_sub_f32_e32 v223, v223, v231
	v_fmac_f32_e32 v231, v223, v175
	s_branch .Lprep2_l0d_1_2

.Lprep2_l0d_1_2:
	global_store_dwordx2 v8, v[140:141], s[0:1] offset:192
	v_mul_f32_e32 v220, v156, v34
	v_mul_f32_e32 v224, v220, v168
	v_add_f32_e32 v168, -1.0, v168
	v_fma_f32 v168, v168, v132, 1.0
	v_mul_f32_e32 v168, v212, v168
	v_mul_f32_e32 v221, v157, v34
	v_mul_f32_e32 v225, v221, v169
	v_add_f32_e32 v169, -1.0, v169
	v_fma_f32 v169, v169, v133, 1.0
	v_mul_f32_e32 v169, v213, v169
	v_mul_f32_e32 v222, v158, v34
	v_mul_f32_e32 v226, v222, v170
	v_add_f32_e32 v170, -1.0, v170
	v_fma_f32 v170, v170, v134, 1.0
	v_mul_f32_e32 v170, v214, v170
	v_mul_f32_e32 v223, v159, v34
	v_mul_f32_e32 v227, v223, v171
	v_add_f32_e32 v171, -1.0, v171
	v_fma_f32 v171, v171, v135, 1.0
	v_mul_f32_e32 v171, v215, v171
	v_cvt_pk_bf16_f32 v88, v184, v185
	v_cvt_pk_bf16_f32 v89, v186, v187
	ds_write_b64 v9, v[88:89] offset:64
	v_cvt_pk_bf16_f32 v88, v168, v169
	v_cvt_pk_bf16_f32 v89, v170, v171
	ds_write_b64 v9, v[88:89] offset:2368
	v_cvt_pk_bf16_f32 v88, v228, v229
	v_cvt_pk_bf16_f32 v89, v230, v231
	ds_write_b64 v9, v[88:89] offset:4672
	v_cvt_pk_bf16_f32 v88, v220, v221
	v_cvt_pk_bf16_f32 v89, v222, v223
	ds_write_b64 v9, v[88:89] offset:6976
	v_cvt_pk_bf16_f32 v88, v224, v225
	v_cvt_pk_bf16_f32 v89, v226, v227
	ds_write_b64 v9, v[88:89] offset:9280
	v_cvt_pk_bf16_f32 v88, v164, v165
	v_cvt_pk_bf16_f32 v89, v166, v167
	ds_write_b64 v9, v[88:89] offset:11584
	s_waitcnt vmcnt(1)
	v_mov_b32_dpp v44, v44 row_newbcast:0 row_mask:0xf bank_mask:0xf
	v_mov_b32_dpp v45, v45 row_newbcast:0 row_mask:0xf bank_mask:0xf
	v_mov_b32_dpp v46, v46 row_newbcast:0 row_mask:0xf bank_mask:0xf
	v_mov_b32_dpp v47, v47 row_newbcast:0 row_mask:0xf bank_mask:0xf
	v_mov_b32_dpp v52, v52 row_newbcast:0 row_mask:0xf bank_mask:0xf
	v_mov_b32_dpp v53, v53 row_newbcast:0 row_mask:0xf bank_mask:0xf
	v_mov_b32_dpp v54, v54 row_newbcast:0 row_mask:0xf bank_mask:0xf
	v_mov_b32_dpp v55, v55 row_newbcast:0 row_mask:0xf bank_mask:0xf
	v_mov_b32_dpp v76, v76 row_newbcast:0 row_mask:0xf bank_mask:0xf
	v_mov_b32_dpp v77, v77 row_newbcast:0 row_mask:0xf bank_mask:0xf
	v_mov_b32_dpp v78, v78 row_newbcast:0 row_mask:0xf bank_mask:0xf
	v_mov_b32_dpp v79, v79 row_newbcast:0 row_mask:0xf bank_mask:0xf
	v_mov_b32_dpp v80, v80 row_newbcast:0 row_mask:0xf bank_mask:0xf
	v_mov_b32_dpp v81, v81 row_newbcast:0 row_mask:0xf bank_mask:0xf
	v_mov_b32_dpp v82, v82 row_newbcast:0 row_mask:0xf bank_mask:0xf
	v_mov_b32_dpp v83, v83 row_newbcast:0 row_mask:0xf bank_mask:0xf
	v_mov_b32_dpp v84, v84 row_newbcast:0 row_mask:0xf bank_mask:0xf
	v_mov_b32_dpp v85, v85 row_newbcast:0 row_mask:0xf bank_mask:0xf
	v_mov_b32_dpp v86, v86 row_newbcast:0 row_mask:0xf bank_mask:0xf
	v_mov_b32_dpp v87, v87 row_newbcast:0 row_mask:0xf bank_mask:0xf
	v_mov_b32_dpp v142, v142 row_newbcast:0 row_mask:0xf bank_mask:0xf
	v_mov_b32_dpp v143, v143 row_newbcast:0 row_mask:0xf bank_mask:0xf
	v_mov_b32_dpp v144, v144 row_newbcast:0 row_mask:0xf bank_mask:0xf
	v_mov_b32_dpp v145, v145 row_newbcast:0 row_mask:0xf bank_mask:0xf
	s_nop 1
	v_mfma_f32_16x16x32_bf16 v[164:167], v[56:59], v[12:15], 0
	v_mfma_f32_16x16x32_bf16 v[168:171], v[64:67], v[20:23], 0
	v_mfma_f32_16x16x32_bf16 v[172:175], v[72:75], v[28:31], 0
	v_mfma_f32_16x16x32_bf16 v[164:167], v[60:63], v[16:19], v[164:167]
	v_mfma_f32_16x16x32_bf16 v[168:171], v[68:71], v[24:27], v[168:171]
	v_and_b32_e32 v42, v5, v42
	v_and_b32_e32 v43, v5, v43
	v_lshlrev_b32_e32 v184, 16, v40
	v_and_b32_e32 v185, 0xffff0000, v40
	v_lshlrev_b32_e32 v220, 16, v42
	v_and_b32_e32 v221, 0xffff0000, v42
	v_sub_f32_e32 v220, v220, v184
	v_sub_f32_e32 v221, v221, v185
	v_fmac_f32_e32 v184, v44, v220
	v_fmac_f32_e32 v185, v45, v221
	v_lshlrev_b32_e32 v186, 16, v41
	v_and_b32_e32 v187, 0xffff0000, v41
	v_lshlrev_b32_e32 v220, 16, v43
	v_and_b32_e32 v221, 0xffff0000, v43
	v_sub_f32_e32 v220, v220, v186
	v_sub_f32_e32 v221, v221, v187
	v_fmac_f32_e32 v186, v46, v220
	v_fmac_f32_e32 v187, v47, v221
	v_and_b32_e32 v50, v5, v50
	v_and_b32_e32 v51, v5, v51
	v_lshlrev_b32_e32 v228, 16, v48
	v_and_b32_e32 v229, 0xffff0000, v48
	v_lshlrev_b32_e32 v220, 16, v50
	v_and_b32_e32 v221, 0xffff0000, v50
	v_sub_f32_e32 v220, v220, v228
	v_sub_f32_e32 v221, v221, v229
	v_fmac_f32_e32 v228, v52, v220
	v_fmac_f32_e32 v229, v53, v221
	v_lshlrev_b32_e32 v230, 16, v49
	v_and_b32_e32 v231, 0xffff0000, v49
	v_lshlrev_b32_e32 v220, 16, v51
	v_and_b32_e32 v221, 0xffff0000, v51
	v_sub_f32_e32 v220, v220, v230
	v_sub_f32_e32 v221, v221, v231
	v_fmac_f32_e32 v230, v54, v220
	v_fmac_f32_e32 v231, v55, v221
	s_nop 7
	v_add_f32_e32 v164, v76, v164
	v_add_f32_e32 v168, v80, v168
	v_add_f32_e32 v172, v142, v172
	v_add_f32_e32 v165, v77, v165
	v_add_f32_e32 v169, v81, v169
	v_add_f32_e32 v173, v143, v173
	v_add_f32_e32 v166, v78, v166
	v_add_f32_e32 v170, v82, v170
	v_add_f32_e32 v174, v144, v174
	v_add_f32_e32 v167, v79, v167
	v_add_f32_e32 v171, v83, v171
	v_add_f32_e32 v175, v145, v175
	v_mul_f32_e32 v164, 0xbfb8aa3b, v164
	v_exp_f32_e32 v164, v164
	s_nop 0
	v_add_f32_e32 v164, 1.0, v164
	v_rcp_f32_e32 v164, v164
	v_mul_f32_e32 v168, 0xbfb8aa3b, v168
	v_exp_f32_e32 v168, v168
	s_nop 0
	v_add_f32_e32 v168, 1.0, v168
	v_rcp_f32_e32 v168, v168
	v_mul_f32_e32 v172, 0xbfb8aa3b, v172
	v_exp_f32_e32 v172, v172
	s_nop 0
	v_add_f32_e32 v172, 1.0, v172
	v_rcp_f32_e32 v172, v172
	v_mul_f32_e32 v165, 0xbfb8aa3b, v165
	v_exp_f32_e32 v165, v165
	s_nop 0
	v_add_f32_e32 v165, 1.0, v165
	v_rcp_f32_e32 v165, v165
	v_mul_f32_e32 v169, 0xbfb8aa3b, v169
	v_exp_f32_e32 v169, v169
	s_nop 0
	v_add_f32_e32 v169, 1.0, v169
	v_rcp_f32_e32 v169, v169
	v_mul_f32_e32 v173, 0xbfb8aa3b, v173
	v_exp_f32_e32 v173, v173
	s_nop 0
	v_add_f32_e32 v173, 1.0, v173
	v_rcp_f32_e32 v173, v173
	v_mul_f32_e32 v166, 0xbfb8aa3b, v166
	v_exp_f32_e32 v166, v166
	s_nop 0
	v_add_f32_e32 v166, 1.0, v166
	v_rcp_f32_e32 v166, v166
	v_mul_f32_e32 v170, 0xbfb8aa3b, v170
	v_exp_f32_e32 v170, v170
	s_nop 0
	v_add_f32_e32 v170, 1.0, v170
	v_rcp_f32_e32 v170, v170
	v_mul_f32_e32 v174, 0xbfb8aa3b, v174
	v_exp_f32_e32 v174, v174
	s_nop 0
	v_add_f32_e32 v174, 1.0, v174
	v_rcp_f32_e32 v174, v174
	v_mul_f32_e32 v167, 0xbfb8aa3b, v167
	v_exp_f32_e32 v167, v167
	s_nop 0
	v_add_f32_e32 v167, 1.0, v167
	v_rcp_f32_e32 v167, v167
	v_mul_f32_e32 v171, 0xbfb8aa3b, v171
	v_exp_f32_e32 v171, v171
	s_nop 0
	v_add_f32_e32 v171, 1.0, v171
	v_rcp_f32_e32 v171, v171
	v_mul_f32_e32 v175, 0xbfb8aa3b, v175
	v_exp_f32_e32 v175, v175
	s_nop 0
	v_add_f32_e32 v175, 1.0, v175
	v_rcp_f32_e32 v175, v175
	v_mul_f32_e32 v164, 0x3f1b4598, v164
	v_mul_f32_e32 v165, 0x3f1b4598, v165
	v_mul_f32_e32 v166, 0x3f1b4598, v166
	v_mul_f32_e32 v167, 0x3f1b4598, v167
	s_cmp_eq_u32 s32, 0
	s_cbranch_scc1 .Lprep2_l0_1_3
	v_lshlrev_b32_e32 v220, 16, v146
	v_and_b32_e32 v221, 0xffff0000, v146
	v_lshlrev_b32_e32 v222, 16, v147
	v_and_b32_e32 v223, 0xffff0000, v147
	v_sub_f32_e32 v220, v220, v228
	v_fmac_f32_e32 v228, v220, v172
	v_sub_f32_e32 v221, v221, v229
	v_fmac_f32_e32 v229, v221, v173
	v_sub_f32_e32 v222, v222, v230
	v_fmac_f32_e32 v230, v222, v174
	v_sub_f32_e32 v223, v223, v231
	v_fmac_f32_e32 v231, v223, v175
	s_branch .Lprep2_l0d_1_3

.Lprep2_l0d_1_3:
	global_store_dwordx2 v8, v[146:147], s[0:1] offset:224
	v_mul_f32_e32 v220, v160, v34
	v_mul_f32_e32 v224, v220, v168
	v_add_f32_e32 v168, -1.0, v168
	v_fma_f32 v168, v168, v84, 1.0
	v_mul_f32_e32 v168, v216, v168
	v_mul_f32_e32 v221, v161, v34
	v_mul_f32_e32 v225, v221, v169
	v_add_f32_e32 v169, -1.0, v169
	v_fma_f32 v169, v169, v85, 1.0
	v_mul_f32_e32 v169, v217, v169
	v_mul_f32_e32 v222, v162, v34
	v_mul_f32_e32 v226, v222, v170
	v_add_f32_e32 v170, -1.0, v170
	v_fma_f32 v170, v170, v86, 1.0
	v_mul_f32_e32 v170, v218, v170
	v_mul_f32_e32 v223, v163, v34
	v_mul_f32_e32 v227, v223, v171
	v_add_f32_e32 v171, -1.0, v171
	v_fma_f32 v171, v171, v87, 1.0
	v_mul_f32_e32 v171, v219, v171
	v_cvt_pk_bf16_f32 v40, v184, v185
	v_cvt_pk_bf16_f32 v41, v186, v187
	ds_write_b64 v9, v[40:41] offset:96
	v_cvt_pk_bf16_f32 v40, v168, v169
	v_cvt_pk_bf16_f32 v41, v170, v171
	ds_write_b64 v9, v[40:41] offset:2400
	v_cvt_pk_bf16_f32 v40, v228, v229
	v_cvt_pk_bf16_f32 v41, v230, v231
	ds_write_b64 v9, v[40:41] offset:4704
	v_cvt_pk_bf16_f32 v40, v220, v221
	v_cvt_pk_bf16_f32 v41, v222, v223
	ds_write_b64 v9, v[40:41] offset:7008
	v_cvt_pk_bf16_f32 v40, v224, v225
	v_cvt_pk_bf16_f32 v41, v226, v227
	ds_write_b64 v9, v[40:41] offset:9312
	v_cvt_pk_bf16_f32 v40, v164, v165
	v_cvt_pk_bf16_f32 v41, v166, v167
	ds_write_b64 v9, v[40:41] offset:11616
	s_waitcnt lgkmcnt(0)
	ds_read_b128 v[148:151], v10 offset:0
	ds_read_b128 v[152:155], v10 offset:1152
	ds_read_b128 v[156:159], v10 offset:2304
	ds_read_b128 v[160:163], v10 offset:3456
	ds_read_b128 v[204:207], v10 offset:4608
	ds_read_b128 v[208:211], v10 offset:5760
	ds_read_b128 v[212:215], v10 offset:6912
	ds_read_b128 v[216:219], v10 offset:8064
	ds_read_b128 v[164:167], v10 offset:9216
	ds_read_b128 v[168:171], v10 offset:10368
	ds_read_b128 v[172:175], v10 offset:11520
	ds_read_b128 v[220:223], v10 offset:12672
	s_add_u32 vcc_lo, s24, 0x10e47000
	s_addc_u32 vcc_hi, s25, 0
	s_waitcnt lgkmcnt(11)
	global_store_dwordx4 v11, v[148:151], vcc offset:128
	s_waitcnt lgkmcnt(10)
	global_store_dwordx4 v32, v[152:155], vcc offset:128
	s_add_u32 vcc_lo, s24, 0x11e47000
	s_addc_u32 vcc_hi, s25, 0
	s_waitcnt lgkmcnt(9)
	global_store_dwordx4 v11, v[156:159], vcc offset:128
	s_waitcnt lgkmcnt(8)
	global_store_dwordx4 v32, v[160:163], vcc offset:128
	s_add_u32 vcc_lo, s24, 0x12e47000
	s_addc_u32 vcc_hi, s25, 0
	s_waitcnt lgkmcnt(7)
	global_store_dwordx4 v11, v[204:207], vcc offset:128
	s_waitcnt lgkmcnt(6)
	global_store_dwordx4 v32, v[208:211], vcc offset:128
	s_add_u32 vcc_lo, s24, 0x13e47000
	s_addc_u32 vcc_hi, s25, 0
	s_waitcnt lgkmcnt(5)
	global_store_dwordx4 v11, v[212:215], vcc offset:128
	s_waitcnt lgkmcnt(4)
	global_store_dwordx4 v32, v[216:219], vcc offset:128
	s_add_u32 vcc_lo, s24, 0x14e47000
	s_addc_u32 vcc_hi, s25, 0
	s_waitcnt lgkmcnt(3)
	global_store_dwordx4 v11, v[164:167], vcc offset:128
	s_waitcnt lgkmcnt(2)
	global_store_dwordx4 v32, v[168:171], vcc offset:128
	s_add_u32 vcc_lo, s24, 0x15e47000
	s_addc_u32 vcc_hi, s25, 0
	s_waitcnt lgkmcnt(1)
	global_store_dwordx4 v11, v[172:175], vcc offset:128
	s_waitcnt lgkmcnt(0)
	global_store_dwordx4 v32, v[220:223], vcc offset:128
	s_add_i32 s13, s13, s26
	s_add_i32 s12, s12, s26
	s_cmpk_gt_i32 s13, 0x3ff
	s_barrier
	s_cbranch_scc1 .LBB0_327

.LBB0_335:
	s_branch .Lprep2_entry
	v_lshl_add_u64 v[28:29], v[24:25], 0, v[2:3]
	global_load_dwordx4 v[4:7], v[28:29], off offset:3072
	v_and_b32_e32 v1, 0xfff, v8
	v_mov_b32_e32 v8, 0
	v_cmp_ne_u32_e64 s[40:41], 0, v1
	v_mov_b32_e32 v10, 0
	v_mov_b32_e32 v11, 0
	v_mov_b32_e32 v12, 0
	v_mov_b32_e32 v13, 0
	s_and_saveexec_b64 s[0:1], s[40:41]
	s_cbranch_execz .LBB0_337
	global_load_dwordx4 v[10:13], v[28:29], off offset:-3840

	.amdhsa_kernel _Z14fwd_megakernel6Params
		.amdhsa_group_segment_fixed_size 65856
		.amdhsa_private_segment_fixed_size 0
		.amdhsa_kernarg_size 488
		.amdhsa_user_sgpr_count 2
		.amdhsa_user_sgpr_dispatch_ptr 0
		.amdhsa_user_sgpr_queue_ptr 0
		.amdhsa_user_sgpr_kernarg_segment_ptr 1
		.amdhsa_user_sgpr_dispatch_id 0
		.amdhsa_user_sgpr_kernarg_preload_length 0
		.amdhsa_user_sgpr_kernarg_preload_offset 0
		.amdhsa_user_sgpr_private_segment_size 0
		.amdhsa_uses_dynamic_stack 0
		.amdhsa_enable_private_segment 0
		.amdhsa_system_sgpr_workgroup_id_x 1
		.amdhsa_system_sgpr_workgroup_id_y 0
		.amdhsa_system_sgpr_workgroup_id_z 0
		.amdhsa_system_sgpr_workgroup_info 0
		.amdhsa_system_vgpr_workitem_id 2
		.amdhsa_next_free_vgpr 238
		.amdhsa_next_free_sgpr 102
		.amdhsa_accum_offset 240
		.amdhsa_reserve_vcc 1
		.amdhsa_float_round_mode_32 0
		.amdhsa_float_round_mode_16_64 0
		.amdhsa_float_denorm_mode_32 3
		.amdhsa_float_denorm_mode_16_64 3
		.amdhsa_dx10_clamp 1
		.amdhsa_ieee_mode 1
		.amdhsa_fp16_overflow 0
		.amdhsa_tg_split 0
		.amdhsa_exception_fp_ieee_invalid_op 0
		.amdhsa_exception_fp_denorm_src 0
		.amdhsa_exception_fp_ieee_div_zero 0
		.amdhsa_exception_fp_ieee_overflow 0
		.amdhsa_exception_fp_ieee_underflow 0
		.amdhsa_exception_fp_ieee_inexact 0
		.amdhsa_exception_int_div_zero 0
	.end_amdhsa_kernel

amdhsa.kernels:
  - .agpr_count:     0
    .args:
      - .offset:         0
        .size:           232
        .value_kind:     by_value
      - .offset:         232
        .size:           4
        .value_kind:     hidden_block_count_x
      - .offset:         236
        .size:           4
        .value_kind:     hidden_block_count_y
      - .offset:         240
        .size:           4
        .value_kind:     hidden_block_count_z
      - .offset:         244
        .size:           2
        .value_kind:     hidden_group_size_x
      - .offset:         246
        .size:           2
        .value_kind:     hidden_group_size_y
      - .offset:         248
        .size:           2
        .value_kind:     hidden_group_size_z
      - .offset:         250
        .size:           2
        .value_kind:     hidden_remainder_x
      - .offset:         252
        .size:           2
        .value_kind:     hidden_remainder_y
      - .offset:         254
        .size:           2
        .value_kind:     hidden_remainder_z
      - .offset:         272
        .size:           8
        .value_kind:     hidden_global_offset_x
      - .offset:         280
        .size:           8
        .value_kind:     hidden_global_offset_y
      - .offset:         288
        .size:           8
        .value_kind:     hidden_global_offset_z
      - .offset:         296
        .size:           2
        .value_kind:     hidden_grid_dims
      - .offset:         320
        .size:           8
        .value_kind:     hidden_multigrid_sync_arg
    .group_segment_fixed_size: 65856
    .kernarg_segment_align: 8
    .kernarg_segment_size: 488
    .language:       OpenCL C
    .language_version:
      - 2
      - 0
    .max_flat_workgroup_size: 256
    .name:           _Z14fwd_megakernel6Params
    .private_segment_fixed_size: 0
    .sgpr_count:     108
    .sgpr_spill_count: 316
    .symbol:         _Z14fwd_megakernel6Params.kd
    .uniform_work_group_size: 1
    .uses_dynamic_stack: false
    .vgpr_count:     238
    .vgpr_spill_count: 0
    .wavefront_size: 64
